# hoisted sumsq loads out of serialized load-wait-store chains in in/up GEMM epilogues; hoisted hgrn norm_g loads out of c3 final stage; relaxed vmcnt ladders in c1/c3 so prefetch waits do not drain pre
# speedup vs baseline: 1.0098x; 1.0098x over previous
; #define LAS __attribute__((address_space(3)))
; __device__ __forceinline__ int tidx() { int t = (int)__builtin_amdgcn_workitem_id_x(); asm volatile("" : "+v"(t)); return t; }
; __device__ __forceinline__ bf16_t f2bf(float f) { return (bf16_t)(cvt_pk_bf16(f, 0.f) & 0xffffu); }
; __device__ __forceinline__ float sigm(float x) { return rcpf_(1.f + __expf(-x)); }
; __device__ __forceinline__ void phase_hgrn_c3(const Params& p, int l, int bid, int nblk, LAS unsigned char* lds) {
;     const int tid = tidx(), wid = tid >> 6, lane = tid & 63, k = tid & 127, sg = tid >> 7;
;     LAS bf16_t* qA = (LAS bf16_t*)lds;
;     LAS bf16_t* qB = (LAS bf16_t*)(lds + 17408);
;     LAS bf16_t* kh = (LAS bf16_t*)(lds + 34816);
;     LAS bf16_t* S0T = (LAS bf16_t*)(lds + 52224);
;     LAS bf16_t* vT = (LAS bf16_t*)(lds + 87040);
;     LAS bf16_t* at = (LAS bf16_t*)(lds + 105472);
;     LAS float* gsum = (LAS float*)(lds + 114688);
;     LAS float* ssq = (LAS float*)(lds + 116736);
;     bf16_t* yc = p.Y + (size_t)2 * MROWS * 1024;
;     bf16_t fr_[16], qr_[16]; u32x4 s0v[4]; bf16x8 vf_[2];
;     const int tt = wid & 3, vh = wid >> 2;
;     ...
;     if (bid < NCHUNK * 8) C3_LOAD(bid);
;     for (int job = bid; job < NCHUNK * 8; job += nblk) {
;     ...
;                 yc[(size_t)(r0 + t) * 1024 + h * 128 + v] = f2bf(acc[vt][j] * rs * p.hgrn_norm_g[l * 128 + v] * (og * sigm(og)));
.LBB0_231:
	s_load_dwordx4 s[44:47], s[0:1], 0x110
	s_add_i32 s4, s41, 7
	s_cmp_gt_u32 s4, 16
	v_ashrrev_i32_e32 v33, 6, v27
	v_lshrrev_b32_e32 v4, 2, v27
	s_cselect_b64 s[78:79], -1, 0
	s_lshl_b32 s38, s72, 7
	v_and_b32_e32 v35, 3, v33
	v_and_b32_e32 v36, 12, v4
	v_ashrrev_i32_e32 v4, 2, v27
	s_waitcnt lgkmcnt(0)
	s_add_u32 s71, s46, 0x4200000
	v_lshlrev_b32_e32 v37, 4, v35
	v_and_b32_e32 v32, 0xffffffc0, v4
	v_and_b32_e32 v4, 15, v27
	v_lshlrev_b32_e32 v100, 4, v26
	v_lshlrev_b32_e32 v33, 1, v33
	v_and_b32_e32 v43, 48, v27
	s_addc_u32 s73, s47, 0
	v_or_b32_e32 v94, v37, v36
	s_add_i32 s4, 0, 0x1c000
	v_and_b32_e32 v39, 2, v33
	v_or_b32_e32 v41, v100, v36
	v_or_b32_e32 v33, v100, v4
	v_add_u32_e32 v36, 0, v43
	s_movk_i32 s19, 0x110
	v_lshl_add_u32 v95, v27, 2, s4
	v_lshl_add_u32 v98, v69, 2, s4
	v_mad_u64_u32 v[46:47], s[4:5], v33, s19, v[36:37]
	v_or_b32_e32 v33, v37, v4
	v_readlane_b32 s6, v255, 4
	v_mad_u32_u24 v47, v33, s19, v36
	v_mul_u32_u24_e32 v33, 0x90, v33
	v_readlane_b32 s28, v255, 5
	v_add_u32_e32 v37, s6, v43
	s_movk_i32 s14, 0x880
	v_add3_u32 v106, s28, v33, v43
	v_lshrrev_b32_e32 v43, 4, v27
	v_mul_lo_u32 v62, v43, s19
	v_add_u32_e32 v43, 0x400, v27
	v_and_b32_e32 v33, 0xffffff00, v27
	v_lshrrev_b32_e32 v43, 4, v43
	v_add_u32_e32 v27, 0x600, v27
	v_lshl_or_b32 v58, v39, 4, v4
	v_lshl_add_u32 v40, v68, 1, s6
	v_or_b32_e32 v38, v32, v4
	v_lshrrev_b32_e32 v30, 4, v30
	v_mul_lo_u32 v63, v43, s19
	v_lshrrev_b32_e32 v27, 4, v27
	s_movk_i32 s18, 0x90
	v_or_b32_e32 v28, 7, v28
	v_and_b32_e32 v48, -8, v29
	v_or_b32_e32 v29, 7, v29
	v_cmp_lt_i32_e64 s[6:7], 0, v26
	v_cmp_lt_i32_e64 s[8:9], 1, v26
	v_cmp_lt_i32_e64 s[10:11], 2, v26
	v_cmp_lt_i32_e64 s[12:13], 3, v26
	v_mul_lo_u32 v43, v26, s14
	v_cmp_le_i32_e64 s[14:15], v39, v26
	v_cmp_lt_i32_e64 s[16:17], v39, v26
	v_or_b32_e32 v26, 16, v58
	v_and_b32_e32 v34, 0x78, v31
	v_lshlrev_b32_e32 v35, 6, v35
	v_readlane_b32 s20, v255, 6
	v_mul_lo_u32 v30, v30, s19
	v_mul_lo_u32 v27, v27, s19
	v_mul_lo_u32 v64, v44, s18
	v_mul_lo_u32 v28, v28, s18
	v_mul_lo_u32 v65, v48, s18
	v_mul_lo_u32 v29, v29, s18
	v_mul_lo_u32 v67, v41, s18
	v_or_b32_e32 v59, 1, v41
	v_or_b32_e32 v60, 2, v41
	v_or_b32_e32 v61, 3, v41
	v_mul_lo_u32 v128, v38, s19
	v_mul_lo_u32 v129, v38, s18
	v_cmp_gt_i32_e64 s[18:19], v58, v41
	v_cmp_gt_i32_e64 s[26:27], v26, v41
	v_lshlrev_b32_e32 v41, 1, v26
	v_lshl_add_u32 v31, v34, 1, 0
	v_add3_u32 v35, s20, v33, v35
	v_ashrrev_i32_e32 v33, 31, v32
	v_or_b32_e32 v43, v43, v69
	v_add_u32_e32 v50, 0x1000, v42
	v_add_u32_e32 v52, 0x2000, v42
	v_add_u32_e32 v54, 0x3000, v42
	v_mul_u32_u24_e32 v66, 0x110, v58
	v_add_u32_e32 v56, s38, v38
	v_ashrrev_i32_e32 v39, 31, v38
	v_or_b32_e32 v109, 1, v94
	v_or_b32_e32 v111, 2, v94
	v_or_b32_e32 v113, 3, v94
	v_lshl_add_u32 v127, v58, 1, s28
	v_add3_u32 v115, s28, v67, v41
	s_ashr_i32 s39, s38, 31
	s_mov_b32 s90, s85
	v_cmp_eq_u32_e64 s[4:5], 0, v4
	v_lshl_add_u32 v107, v43, 1, 0
	v_ashrrev_i32_e32 v43, 31, v42
	v_ashrrev_i32_e32 v51, 31, v50
	v_ashrrev_i32_e32 v53, 31, v52
	v_ashrrev_i32_e32 v55, 31, v54
	v_ashrrev_i32_e32 v45, 31, v44
	v_ashrrev_i32_e32 v49, 31, v48
	v_lshl_add_u32 v108, v94, 2, s20
	v_ashrrev_i32_e32 v57, 31, v56
	v_lshl_add_u32 v110, v109, 2, s20
	v_lshl_add_u32 v112, v111, 2, s20
	v_lshl_add_u32 v114, v113, 2, s20
	v_cmp_gt_i32_e64 s[20:21], v58, v59
	v_cmp_gt_i32_e64 s[22:23], v58, v60
	v_cmp_gt_i32_e64 s[24:25], v58, v61
	v_cmp_gt_i32_e64 s[28:29], v26, v59
	v_add_u32_e32 v116, 0x90, v115
	v_cmp_gt_i32_e64 s[30:31], v26, v60
	v_add_u32_e32 v117, 0x120, v115
	v_cmp_gt_i32_e64 s[34:35], v26, v61
	v_add_u32_e32 v118, 0x1b0, v115
	v_lshl_add_u64 v[58:59], v[38:39], 0, s[38:39]
	s_lshl_b32 s82, s42, 3
	s_lshl_b32 s83, s70, 3
	s_lshl_b32 s84, s42, 7
	s_lshl_b32 s85, s70, 7
	s_add_i32 s46, s70, s42
	v_lshlrev_b32_e32 v4, 1, v4
	v_lshlrev_b64 v[60:61], 1, v[32:33]
	v_add_u32_e32 v119, v31, v62
	v_add_u32_e32 v120, v31, v30
	v_add_u32_e32 v121, v31, v63
	v_add_u32_e32 v122, v31, v27
	v_add_u32_e32 v123, v40, v64
	v_add_u32_e32 v124, v40, v28
	v_add_u32_e32 v125, v40, v65
	v_add_u32_e32 v126, v40, v29
	v_lshlrev_b32_e32 v62, 1, v34
	v_add_u32_e32 v127, v127, v67
	v_add_u32_e32 v128, v36, v128
	v_add_u32_e32 v129, v37, v129
	v_lshlrev_b64 v[64:65], 1, v[38:39]
	v_add_u32_e32 v130, v36, v66
	v_add_u32_e32 v131, v35, v68
	s_mov_b32 s86, s70
	s_load_dwordx2 s[98:99], s[0:1], 0x80
	v_lshlrev_b32_e32 v176, 2, v56
	s_waitcnt lgkmcnt(0)
	global_load_dword v172, v176, s[98:99]
	global_load_dword v173, v176, s[98:99] offset:64
	global_load_dword v174, v176, s[98:99] offset:128
	global_load_dword v175, v176, s[98:99] offset:192
	s_waitcnt vmcnt(0)
	s_branch .LBB0_233
; __device__ __forceinline__ float bf2f(bf16_t b) { return __uint_as_float(((unsigned)b) << 16); }
; __device__ __forceinline__ bf16_t f2bf(float f) { return (bf16_t)(cvt_pk_bf16(f, 0.f) & 0xffffu); }
; __device__ __forceinline__ float sigm(float x) { return rcpf_(1.f + __expf(-x)); }
; __device__ __forceinline__ void phase_hgrn_c3(const Params& p, int l, int bid, int nblk, LAS unsigned char* lds) {
;     ...
;         __syncthreads();
; #pragma unroll
;         for (int j = 0; j < 4; ++j) {
;             const int t = 16 * tt + (lane >> 4) * 4 + j;
;             const float rs = rsqrtf((ssq[t] + ssq[64 + t]) * (1.f / 128.f) + EPS);
; #pragma unroll
;             for (int vt = 0; vt < 4; ++vt) {
;                 const int v = 16 * (vh * 4 + vt) + (lane & 15);
;                 const float og = bf2f(og_[j * 4 + vt]);
;                 yc[(size_t)(r0 + t) * 1024 + h * 128 + v] = f2bf(acc[vt][j] * rs * p.hgrn_norm_g[l * 128 + v] * (og * sigm(og)));
;             }
;         }
.LBB0_232:
	s_or_b64 exec, exec, s[38:39]
	s_waitcnt lgkmcnt(0)
	s_barrier
	ds_read2st64_b32 v[148:149], v108 offset1:1
	s_load_dwordx2 s[80:81], s[0:1], 0x80
	s_waitcnt vmcnt(15)
	v_lshlrev_b32_e32 v147, 16, v147
	s_add_i32 s86, s86, s42
	v_ashrrev_i32_e32 v67, 31, v66
	s_waitcnt lgkmcnt(0)
	v_add_f32_e32 v63, v148, v149
	v_fmamk_f32 v63, v63, 0x3c000000, v236
	v_cmp_gt_f32_e32 vcc, s37, v63
	v_mul_f32_e32 v148, 0x4b800000, v63
	s_add_u32 s38, s71, s50
	v_cndmask_b32_e32 v63, v63, v148, vcc
	v_rsq_f32_e32 v63, v63
	s_addc_u32 s39, s73, 0
	v_lshlrev_b64 v[66:67], 11, v[66:67]
	v_lshl_add_u64 v[66:67], s[38:39], 0, v[66:67]
	v_mul_f32_e32 v148, 0x45800000, v63
	v_cndmask_b32_e32 v63, v63, v148, vcc
	v_lshl_add_u64 v[148:149], v[56:57], 2, s[80:81]
	v_mul_f32_e32 v150, v38, v63
	v_mov_b32_e32 v38, v172
	v_mul_f32_e32 v149, 0xbfb8aa3b, v147
	v_exp_f32_e32 v149, v149
	v_lshl_add_u64 v[66:67], v[66:67], 0, v[64:65]
	s_waitcnt vmcnt(14)
	v_lshlrev_b32_e32 v145, 16, v145
	s_waitcnt vmcnt(13)
	v_lshlrev_b32_e32 v144, 16, v144
	v_add_f32_e32 v149, 1.0, v149
	v_rcp_f32_e32 v149, v149
	s_waitcnt vmcnt(12)
	v_lshlrev_b32_e32 v143, 16, v143
	s_add_i32 s83, s83, s82
	s_add_i32 s85, s85, s84
	v_mul_f32_e32 v147, v149, v147
	v_mul_f32_e32 v149, v34, v63
	s_add_i32 s46, s46, s42
	s_cmpk_lt_i32 s86, 0x840
	s_waitcnt vmcnt(0)
	v_mul_f32_e32 v148, v38, v150
	v_mul_f32_e32 v147, v147, v148
	v_cvt_pk_bf16_f32 v147, v147, v5
	global_store_short v[66:67], v147, off
	v_lshlrev_b32_e32 v148, 16, v146
	v_lshl_add_u64 v[146:147], v[58:59], 2, s[80:81]
	v_mov_b32_e32 v34, v173
	v_mul_f32_e32 v150, 0xbfb8aa3b, v148
	v_exp_f32_e32 v150, v150
	v_mul_f32_e32 v149, v34, v149
	v_add_f32_e32 v150, 1.0, v150
	v_rcp_f32_e32 v150, v150
	s_nop 0
	v_mul_f32_e32 v148, v150, v148
	v_mul_f32_e32 v148, v148, v149
	v_cvt_pk_bf16_f32 v148, v148, v5
	global_store_short v[66:67], v148, off offset:32
	v_mul_f32_e32 v148, v30, v63
	v_mov_b32_e32 v30, v174
	v_mul_f32_e32 v63, v26, v63
	v_mov_b32_e32 v26, v175
	v_mul_f32_e32 v149, 0xbfb8aa3b, v145
	v_exp_f32_e32 v149, v149
	v_mul_f32_e32 v148, v30, v148
	v_add_f32_e32 v149, 1.0, v149
	v_rcp_f32_e32 v149, v149
	v_mul_f32_e32 v63, v63, v26
	v_mul_f32_e32 v145, v149, v145
	v_mul_f32_e32 v145, v145, v148
	v_cvt_pk_bf16_f32 v145, v145, v5
	global_store_short v[66:67], v145, off offset:64
	v_mul_f32_e32 v145, 0xbfb8aa3b, v144
	v_exp_f32_e32 v145, v145
	s_nop 0
	v_add_f32_e32 v145, 1.0, v145
	v_rcp_f32_e32 v145, v145
	s_nop 0
	v_mul_f32_e32 v144, v145, v144
	v_mul_f32_e32 v63, v144, v63
	v_cvt_pk_bf16_f32 v63, v63, v5
	global_store_short v[66:67], v63, off offset:96
	ds_read2st64_b32 v[66:67], v110 offset1:1
	v_mul_f32_e32 v144, 0xbfb8aa3b, v143
	v_exp_f32_e32 v144, v144
	s_waitcnt lgkmcnt(0)
	v_add_f32_e32 v63, v66, v67
	v_fmamk_f32 v63, v63, 0x3c000000, v236
	v_cmp_gt_f32_e32 vcc, s37, v63
	v_mul_f32_e32 v66, 0x4b800000, v63
	v_add_f32_e32 v144, 1.0, v144
	v_cndmask_b32_e32 v63, v63, v66, vcc
	v_rsq_f32_e32 v63, v63
	v_rcp_f32_e32 v144, v144
	v_mul_f32_e32 v66, 0x45800000, v63
	v_cndmask_b32_e32 v63, v63, v66, vcc
	v_or_b32_e32 v66, s87, v109
	v_ashrrev_i32_e32 v67, 31, v66
	v_mul_f32_e32 v39, v39, v63
	v_lshlrev_b64 v[66:67], 11, v[66:67]
	v_mul_f32_e32 v39, v38, v39
	v_mul_f32_e32 v143, v144, v143
	v_lshl_add_u64 v[66:67], s[38:39], 0, v[66:67]
	v_mul_f32_e32 v39, v143, v39
	v_cvt_pk_bf16_f32 v39, v39, v5
	v_lshl_add_u64 v[66:67], v[66:67], 0, v[64:65]
	global_store_short v[66:67], v39, off
	v_lshlrev_b32_e32 v39, 16, v142
	v_mul_f32_e32 v142, 0xbfb8aa3b, v39
	v_exp_f32_e32 v142, v142
	v_mul_f32_e32 v35, v35, v63
	v_mul_f32_e32 v35, v34, v35
	v_mul_f32_e32 v31, v31, v63
	v_add_f32_e32 v142, 1.0, v142
	v_rcp_f32_e32 v142, v142
	v_mul_f32_e32 v31, v30, v31
	v_mul_f32_e32 v27, v27, v63
	v_mul_f32_e32 v27, v26, v27
	v_mul_f32_e32 v39, v142, v39
	v_mul_f32_e32 v35, v39, v35
	v_cvt_pk_bf16_f32 v35, v35, v5
	global_store_short v[66:67], v35, off offset:32
	v_lshlrev_b32_e32 v35, 16, v141
	v_mul_f32_e32 v39, 0xbfb8aa3b, v35
	v_exp_f32_e32 v39, v39
	s_nop 0
	v_add_f32_e32 v39, 1.0, v39
	v_rcp_f32_e32 v39, v39
	s_nop 0
	v_mul_f32_e32 v35, v39, v35
	v_mul_f32_e32 v31, v35, v31
	v_cvt_pk_bf16_f32 v31, v31, v5
	global_store_short v[66:67], v31, off offset:64
	v_lshlrev_b32_e32 v31, 16, v140
	v_mul_f32_e32 v35, 0xbfb8aa3b, v31
	v_exp_f32_e32 v35, v35
	s_nop 0
	v_add_f32_e32 v35, 1.0, v35
	v_rcp_f32_e32 v35, v35
	s_nop 0
	v_mul_f32_e32 v31, v35, v31
	v_mul_f32_e32 v27, v31, v27
	v_cvt_pk_bf16_f32 v27, v27, v5
	global_store_short v[66:67], v27, off offset:96
	ds_read2st64_b32 v[66:67], v112 offset1:1
	s_waitcnt lgkmcnt(0)
; __device__ __forceinline__ float bf2f(bf16_t b) { return __uint_as_float(((unsigned)b) << 16); }
; __device__ __forceinline__ bf16_t f2bf(float f) { return (bf16_t)(cvt_pk_bf16(f, 0.f) & 0xffffu); }
; __device__ __forceinline__ float sigm(float x) { return rcpf_(1.f + __expf(-x)); }
; __device__ __forceinline__ void phase_hgrn_c3(const Params& p, int l, int bid, int nblk, LAS unsigned char* lds) {
;     ...
; #pragma unroll
;         for (int j = 0; j < 4; ++j) {
;             const int t = 16 * tt + (lane >> 4) * 4 + j;
;             const float rs = rsqrtf((ssq[t] + ssq[64 + t]) * (1.f / 128.f) + EPS);
; #pragma unroll
;             for (int vt = 0; vt < 4; ++vt) {
;                 const int v = 16 * (vh * 4 + vt) + (lane & 15);
;                 const float og = bf2f(og_[j * 4 + vt]);
;                 yc[(size_t)(r0 + t) * 1024 + h * 128 + v] = f2bf(acc[vt][j] * rs * p.hgrn_norm_g[l * 128 + v] * (og * sigm(og)));
;             }
;         }
	v_add_f32_e32 v27, v66, v67
	v_fmamk_f32 v27, v27, 0x3c000000, v236
	v_cmp_gt_f32_e32 vcc, s37, v27
	v_mul_f32_e32 v31, 0x4b800000, v27
	v_or_b32_e32 v66, s87, v111
	v_cndmask_b32_e32 v27, v27, v31, vcc
	v_rsq_f32_e32 v27, v27
	v_ashrrev_i32_e32 v67, 31, v66
	v_lshlrev_b64 v[66:67], 11, v[66:67]
	v_lshl_add_u64 v[66:67], s[38:39], 0, v[66:67]
	v_mul_f32_e32 v31, 0x45800000, v27
	v_cndmask_b32_e32 v27, v27, v31, vcc
	v_lshlrev_b32_e32 v31, 16, v139
	v_mul_f32_e32 v39, 0xbfb8aa3b, v31
	v_exp_f32_e32 v39, v39
	v_mul_f32_e32 v35, v40, v27
	v_mul_f32_e32 v35, v38, v35
	v_lshl_add_u64 v[66:67], v[66:67], 0, v[64:65]
	v_add_f32_e32 v39, 1.0, v39
	v_rcp_f32_e32 v39, v39
	v_mul_f32_e32 v32, v32, v27
	v_mul_f32_e32 v32, v30, v32
	v_mul_f32_e32 v31, v39, v31
	v_mul_f32_e32 v31, v31, v35
	v_cvt_pk_bf16_f32 v31, v31, v5
	global_store_short v[66:67], v31, off
	v_lshlrev_b32_e32 v31, 16, v138
	v_mul_f32_e32 v35, v36, v27
	v_mul_f32_e32 v36, 0xbfb8aa3b, v31
	v_exp_f32_e32 v36, v36
	v_mul_f32_e32 v35, v34, v35
	v_mul_f32_e32 v27, v28, v27
	v_mul_f32_e32 v27, v26, v27
	v_add_f32_e32 v36, 1.0, v36
	v_rcp_f32_e32 v36, v36
	s_nop 0
	v_mul_f32_e32 v31, v36, v31
	v_mul_f32_e32 v31, v31, v35
	v_cvt_pk_bf16_f32 v31, v31, v5
	global_store_short v[66:67], v31, off offset:32
	v_lshlrev_b32_e32 v31, 16, v137
	v_mul_f32_e32 v35, 0xbfb8aa3b, v31
	v_exp_f32_e32 v35, v35
	s_nop 0
	v_add_f32_e32 v35, 1.0, v35
	v_rcp_f32_e32 v35, v35
	s_nop 0
	v_mul_f32_e32 v31, v35, v31
	v_mul_f32_e32 v31, v31, v32
	v_cvt_pk_bf16_f32 v31, v31, v5
	global_store_short v[66:67], v31, off offset:64
	v_lshlrev_b32_e32 v31, 16, v136
	v_mul_f32_e32 v28, 0xbfb8aa3b, v31
	v_exp_f32_e32 v28, v28
	s_nop 0
	v_add_f32_e32 v28, 1.0, v28
	v_rcp_f32_e32 v28, v28
	s_nop 0
	v_mul_f32_e32 v28, v28, v31
	v_mul_f32_e32 v27, v28, v27
	v_cvt_pk_bf16_f32 v27, v27, v5
	global_store_short v[66:67], v27, off offset:96
	ds_read2st64_b32 v[66:67], v114 offset1:1
	s_waitcnt lgkmcnt(0)
	v_add_f32_e32 v27, v66, v67
	v_fmamk_f32 v27, v27, 0x3c000000, v236
	v_cmp_gt_f32_e32 vcc, s37, v27
	v_mul_f32_e32 v28, 0x4b800000, v27
	v_or_b32_e32 v66, s87, v113
	v_cndmask_b32_e32 v27, v27, v28, vcc
	v_rsq_f32_e32 v27, v27
	v_ashrrev_i32_e32 v67, 31, v66
	v_lshlrev_b64 v[66:67], 11, v[66:67]
	v_lshl_add_u64 v[66:67], s[38:39], 0, v[66:67]
	v_mul_f32_e32 v28, 0x45800000, v27
	v_cndmask_b32_e32 v27, v27, v28, vcc
	v_lshlrev_b32_e32 v28, 16, v135
	v_mul_f32_e32 v32, 0xbfb8aa3b, v28
	v_exp_f32_e32 v32, v32
	v_mul_f32_e32 v31, v41, v27
	v_mul_f32_e32 v31, v38, v31
	v_lshl_add_u64 v[38:39], v[66:67], 0, v[64:65]
	v_add_f32_e32 v32, 1.0, v32
	v_rcp_f32_e32 v32, v32
	s_nop 0
	v_mul_f32_e32 v28, v32, v28
	v_mul_f32_e32 v28, v28, v31
	v_cvt_pk_bf16_f32 v28, v28, v5
	global_store_short v[38:39], v28, off
	v_lshlrev_b32_e32 v28, 16, v134
	v_mul_f32_e32 v32, 0xbfb8aa3b, v28
	v_exp_f32_e32 v32, v32
	v_mul_f32_e32 v31, v37, v27
	v_mul_f32_e32 v31, v34, v31
	v_add_f32_e32 v32, 1.0, v32
	v_rcp_f32_e32 v32, v32
	s_nop 0
	v_mul_f32_e32 v28, v32, v28
	v_mul_f32_e32 v28, v28, v31
	v_cvt_pk_bf16_f32 v28, v28, v5
	global_store_short v[38:39], v28, off offset:32
	v_lshlrev_b32_e32 v28, 16, v133
	v_mul_f32_e32 v31, v33, v27
	v_mul_f32_e32 v30, v30, v31
	v_mul_f32_e32 v31, 0xbfb8aa3b, v28
	v_exp_f32_e32 v31, v31
	v_mul_f32_e32 v27, v29, v27
	v_mul_f32_e32 v26, v26, v27
	v_add_f32_e32 v31, 1.0, v31
	v_rcp_f32_e32 v31, v31
	s_nop 0
	v_mul_f32_e32 v28, v31, v28
	v_mul_f32_e32 v28, v28, v30
	v_cvt_pk_bf16_f32 v28, v28, v5
	global_store_short v[38:39], v28, off offset:64
	v_lshlrev_b32_e32 v28, 16, v132
	v_mul_f32_e32 v27, 0xbfb8aa3b, v28
	v_exp_f32_e32 v27, v27
	s_nop 0
	v_add_f32_e32 v27, 1.0, v27
	v_rcp_f32_e32 v27, v27
	s_nop 0
	v_mul_f32_e32 v27, v27, v28
	v_mul_f32_e32 v26, v27, v26
	v_cvt_pk_bf16_f32 v26, v26, v5
	global_store_short v[38:39], v26, off offset:96
	s_barrier
	s_cbranch_scc0 .LBB0_257

; __device__ __forceinline__ float bf2f(bf16_t b) { return __uint_as_float(((unsigned)b) << 16); }
; __device__ __forceinline__ float rcpf_(float x) { return __builtin_amdgcn_rcpf(x); }
; __device__ __forceinline__ void phase_hgrn_c3(const Params& p, int l, int bid, int nblk, LAS unsigned char* lds) {
;     ...
; #pragma unroll
;         for (int j = 0; j < 4; ++j)
; #pragma unroll
;             for (int vt = 0; vt < 4; ++vt) og_[j * 4 + vt] = p.P[(size_t)(r0 + 16 * tt + (lane >> 4) * 4 + j) * NIN + C_GC + h * 128 + 16 * (vh * 4 + vt) + (lane & 15)];
;         float bl[16], kk[16]; float run = 0.f;
; #pragma unroll
;         for (int i = 0; i < 16; ++i) {
;             const float z = bf2f(fr_[i]);
;             const float sg1 = rcpf_(1.f + __expf(-z)), om = rcpf_(1.f + __expf(z));
;             const float f = lb + (1.f - lb) * sg1; run += fmaxf(__logf(f), -60.f); bl[i] = run; kk[i] = (1.f - lb) * om;
;         }
.LBB0_235:
	s_and_b32 s87, s83, 0xffffffc0
	v_or_b32_e32 v66, s87, v94
	v_mov_b64_e32 v[28:29], s[44:45]
	v_mad_i64_i32 v[30:31], s[80:81], v66, s43, v[28:29]
	s_lshl_b32 s50, s38, 1
	v_lshl_add_u64 v[30:31], v[30:31], 0, s[50:51]
	v_lshl_add_u64 v[30:31], v[30:31], 0, v[4:5]
	v_lshl_add_u64 v[30:31], v[30:31], 0, v[60:61]
	s_mov_b64 s[74:75], 0x3800
	v_lshl_add_u64 v[32:33], v[30:31], 0, s[74:75]
	v_add_co_u32_e32 v30, vcc, 0x3000, v30
	v_or_b32_e32 v27, 1, v66
	s_nop 0
	v_addc_co_u32_e32 v31, vcc, 0, v31, vcc
	global_load_ushort v147, v[30:31], off offset:2048
	global_load_ushort v146, v[32:33], off offset:32
	global_load_ushort v145, v[32:33], off offset:64
	global_load_ushort v144, v[32:33], off offset:96
	v_mad_i64_i32 v[30:31], s[38:39], v27, s43, v[28:29]
	v_lshl_add_u64 v[30:31], v[30:31], 0, s[50:51]
	v_lshl_add_u64 v[30:31], v[30:31], 0, v[4:5]
	v_lshl_add_u64 v[30:31], v[30:31], 0, v[60:61]
	v_lshl_add_u64 v[32:33], v[30:31], 0, s[74:75]
	v_add_co_u32_e32 v30, vcc, s95, v30
	v_or_b32_e32 v27, 2, v66
	s_nop 0
	v_addc_co_u32_e32 v31, vcc, 0, v31, vcc
	global_load_ushort v143, v[30:31], off offset:2048
	global_load_ushort v142, v[32:33], off offset:32
	global_load_ushort v141, v[32:33], off offset:64
	global_load_ushort v140, v[32:33], off offset:96
	v_mad_i64_i32 v[30:31], s[38:39], v27, s43, v[28:29]
	v_lshl_add_u64 v[30:31], v[30:31], 0, s[50:51]
	v_or_b32_e32 v27, 3, v66
	v_lshl_add_u64 v[30:31], v[30:31], 0, v[4:5]
	v_mad_i64_i32 v[28:29], s[38:39], v27, s43, v[28:29]
	v_lshl_add_u64 v[30:31], v[30:31], 0, v[60:61]
	v_lshl_add_u64 v[28:29], v[28:29], 0, s[50:51]
	v_lshl_add_u64 v[32:33], v[30:31], 0, s[74:75]
	v_add_co_u32_e32 v30, vcc, s95, v30
	v_lshl_add_u64 v[28:29], v[28:29], 0, v[4:5]
	s_nop 0
	v_addc_co_u32_e32 v31, vcc, 0, v31, vcc
	v_lshl_add_u64 v[28:29], v[28:29], 0, v[60:61]
	global_load_ushort v139, v[30:31], off offset:2048
	global_load_ushort v138, v[32:33], off offset:32
	global_load_ushort v137, v[32:33], off offset:64
	global_load_ushort v136, v[32:33], off offset:96
	v_lshl_add_u64 v[30:31], v[28:29], 0, s[74:75]
	v_add_co_u32_e32 v28, vcc, s95, v28
	s_waitcnt vmcnt(63)
	v_lshlrev_b32_e32 v148, 16, v72
	v_addc_co_u32_e32 v29, vcc, 0, v29, vcc
	global_load_ushort v135, v[28:29], off offset:2048
	global_load_ushort v134, v[30:31], off offset:32
	global_load_ushort v133, v[30:31], off offset:64
	global_load_ushort v132, v[30:31], off offset:96
	v_mul_f32_e32 v28, 0xbfb8aa3b, v148
	v_exp_f32_e32 v28, v28
	v_sub_f32_e32 v27, 1.0, v67
	s_waitcnt vmcnt(63)
	v_lshlrev_b32_e32 v149, 16, v75
	s_waitcnt vmcnt(63)
	v_lshlrev_b32_e32 v150, 16, v76
	v_add_f32_e32 v28, 1.0, v28
	v_rcp_f32_e32 v28, v28
	s_waitcnt vmcnt(63)
	v_lshlrev_b32_e32 v151, 16, v77
	s_waitcnt vmcnt(61)
	v_lshlrev_b32_e32 v152, 16, v80
	s_waitcnt vmcnt(60)
	v_lshlrev_b32_e32 v153, 16, v83
	v_fma_f32 v28, v28, v27, v67
	v_cmp_gt_f32_e32 vcc, s37, v28
	s_waitcnt vmcnt(59)
	v_lshlrev_b32_e32 v154, 16, v84
	s_waitcnt vmcnt(58)
	v_lshlrev_b32_e32 v155, 16, v85
	v_cndmask_b32_e64 v29, 0, 32, vcc
	v_ldexp_f32 v28, v28, v29
	v_log_f32_e32 v28, v28
	s_waitcnt vmcnt(53)
	v_lshlrev_b32_e32 v156, 16, v88
	s_waitcnt vmcnt(52)
	v_lshlrev_b32_e32 v157, 16, v91
	s_waitcnt vmcnt(51)
	v_lshlrev_b32_e32 v158, 16, v92
	v_mul_f32_e32 v29, 0x3f317217, v28
	v_fma_f32 v29, v28, s96, -v29
	v_fmac_f32_e32 v29, 0x3377d1cf, v28
	v_fmac_f32_e32 v29, 0x3f317217, v28
	v_cmp_lt_f32_e64 s[38:39], |v28|, s58
	s_waitcnt vmcnt(50)
	v_lshlrev_b32_e32 v159, 16, v93
	s_waitcnt vmcnt(45)
	v_lshlrev_b32_e32 v160, 16, v102
	v_cndmask_b32_e64 v28, v28, v29, s[38:39]
	v_cndmask_b32_e32 v29, 0, v242, vcc
	v_sub_f32_e32 v28, v28, v29
	v_mul_f32_e32 v29, 0xbfb8aa3b, v149
	v_exp_f32_e32 v29, v29
	v_max_f32_e32 v28, 0xc2700000, v28
	v_add_f32_e32 v28, 0, v28
	s_waitcnt vmcnt(44)
	v_lshlrev_b32_e32 v161, 16, v103
	v_add_f32_e32 v29, 1.0, v29
	v_rcp_f32_e32 v29, v29
	s_waitcnt vmcnt(43)
	v_lshlrev_b32_e32 v162, 16, v104
	v_fma_f32 v29, v29, v27, v67
	v_cmp_gt_f32_e32 vcc, s37, v29
	s_nop 1
	v_cndmask_b32_e64 v30, 0, 32, vcc
	v_ldexp_f32 v29, v29, v30
	v_log_f32_e32 v29, v29
	s_nop 0
	v_mul_f32_e32 v30, 0x3f317217, v29
	v_fma_f32 v30, v29, s96, -v30
	v_fmac_f32_e32 v30, 0x3377d1cf, v29
	v_fmac_f32_e32 v30, 0x3f317217, v29
	v_cmp_lt_f32_e64 s[38:39], |v29|, s58
	s_nop 1
	v_cndmask_b32_e64 v29, v29, v30, s[38:39]
	v_cndmask_b32_e32 v30, 0, v242, vcc
	v_sub_f32_e32 v29, v29, v30
	v_max_f32_e32 v29, 0xc2700000, v29
	v_add_f32_e32 v31, v29, v28
	v_mul_f32_e32 v29, 0xbfb8aa3b, v150
	v_exp_f32_e32 v29, v29
	s_nop 0
	v_add_f32_e32 v29, 1.0, v29
	v_rcp_f32_e32 v29, v29
	s_nop 0
	v_fma_f32 v29, v29, v27, v67
	v_cmp_gt_f32_e32 vcc, s37, v29
	s_nop 1
	v_cndmask_b32_e64 v30, 0, 32, vcc
	v_ldexp_f32 v29, v29, v30
	v_log_f32_e32 v29, v29
	s_nop 0
	v_mul_f32_e32 v30, 0x3f317217, v29
	v_fma_f32 v30, v29, s96, -v30
	v_fmac_f32_e32 v30, 0x3377d1cf, v29
	v_fmac_f32_e32 v30, 0x3f317217, v29
	v_cmp_lt_f32_e64 s[38:39], |v29|, s58
	s_nop 1
	v_cndmask_b32_e64 v29, v29, v30, s[38:39]
	v_cndmask_b32_e32 v30, 0, v242, vcc
	v_sub_f32_e32 v29, v29, v30
	v_mul_f32_e32 v30, 0xbfb8aa3b, v151
	v_exp_f32_e32 v30, v30
	v_max_f32_e32 v29, 0xc2700000, v29
	v_add_f32_e32 v29, v29, v31
	v_add_f32_e32 v30, 1.0, v30
	v_rcp_f32_e32 v30, v30
	s_nop 0
	v_fma_f32 v30, v30, v27, v67
	v_cmp_gt_f32_e32 vcc, s37, v30
	s_nop 1
	v_cndmask_b32_e64 v32, 0, 32, vcc
	v_ldexp_f32 v30, v30, v32
	v_log_f32_e32 v30, v30
	s_nop 0
	v_mul_f32_e32 v32, 0x3f317217, v30
	v_fma_f32 v32, v30, s96, -v32
	v_fmac_f32_e32 v32, 0x3377d1cf, v30
	v_fmac_f32_e32 v32, 0x3f317217, v30
	v_cmp_lt_f32_e64 s[38:39], |v30|, s58
	s_nop 1
	v_cndmask_b32_e64 v30, v30, v32, s[38:39]
; __device__ __forceinline__ float bf2f(bf16_t b) { return __uint_as_float(((unsigned)b) << 16); }
; __device__ __forceinline__ float rcpf_(float x) { return __builtin_amdgcn_rcpf(x); }
; __device__ __forceinline__ void phase_hgrn_c3(const Params& p, int l, int bid, int nblk, LAS unsigned char* lds) {
;     ...
;         float bl[16], kk[16]; float run = 0.f;
; #pragma unroll
;         for (int i = 0; i < 16; ++i) {
;             const float z = bf2f(fr_[i]);
;             const float sg1 = rcpf_(1.f + __expf(-z)), om = rcpf_(1.f + __expf(z));
;             const float f = lb + (1.f - lb) * sg1; run += fmaxf(__logf(f), -60.f); bl[i] = run; kk[i] = (1.f - lb) * om;
;         }
	v_cndmask_b32_e32 v32, 0, v242, vcc
	v_sub_f32_e32 v30, v30, v32
	v_max_f32_e32 v30, 0xc2700000, v30
	v_add_f32_e32 v33, v30, v29
	v_mul_f32_e32 v30, 0xbfb8aa3b, v152
	v_exp_f32_e32 v30, v30
	s_nop 0
	v_add_f32_e32 v30, 1.0, v30
	v_rcp_f32_e32 v30, v30
	s_nop 0
	v_fma_f32 v30, v30, v27, v67
	v_cmp_gt_f32_e32 vcc, s37, v30
	s_nop 1
	v_cndmask_b32_e64 v32, 0, 32, vcc
	v_ldexp_f32 v30, v30, v32
	v_log_f32_e32 v30, v30
	s_nop 0
	v_mul_f32_e32 v32, 0x3f317217, v30
	v_fma_f32 v32, v30, s96, -v32
	v_fmac_f32_e32 v32, 0x3377d1cf, v30
	v_fmac_f32_e32 v32, 0x3f317217, v30
	v_cmp_lt_f32_e64 s[38:39], |v30|, s58
	s_nop 1
	v_cndmask_b32_e64 v30, v30, v32, s[38:39]
	v_cndmask_b32_e32 v32, 0, v242, vcc
	v_sub_f32_e32 v30, v30, v32
	v_mul_f32_e32 v32, 0xbfb8aa3b, v153
	v_exp_f32_e32 v32, v32
	v_max_f32_e32 v30, 0xc2700000, v30
	v_add_f32_e32 v30, v30, v33
	v_add_f32_e32 v32, 1.0, v32
	v_rcp_f32_e32 v32, v32
	s_nop 0
	v_fma_f32 v32, v32, v27, v67
	v_cmp_gt_f32_e32 vcc, s37, v32
	s_nop 1
	v_cndmask_b32_e64 v34, 0, 32, vcc
	v_ldexp_f32 v32, v32, v34
	v_log_f32_e32 v32, v32
	s_nop 0
	v_mul_f32_e32 v34, 0x3f317217, v32
	v_fma_f32 v34, v32, s96, -v34
	v_fmac_f32_e32 v34, 0x3377d1cf, v32
	v_fmac_f32_e32 v34, 0x3f317217, v32
	v_cmp_lt_f32_e64 s[38:39], |v32|, s58
	s_nop 1
	v_cndmask_b32_e64 v32, v32, v34, s[38:39]
	v_cndmask_b32_e32 v34, 0, v242, vcc
	v_sub_f32_e32 v32, v32, v34
	v_max_f32_e32 v32, 0xc2700000, v32
	v_add_f32_e32 v35, v32, v30
	v_mul_f32_e32 v32, 0xbfb8aa3b, v154
	v_exp_f32_e32 v32, v32
	s_nop 0
	v_add_f32_e32 v32, 1.0, v32
	v_rcp_f32_e32 v32, v32
	s_nop 0
	v_fma_f32 v32, v32, v27, v67
	v_cmp_gt_f32_e32 vcc, s37, v32
	s_nop 1
	v_cndmask_b32_e64 v34, 0, 32, vcc
	v_ldexp_f32 v32, v32, v34
	v_log_f32_e32 v32, v32
	s_nop 0
	v_mul_f32_e32 v34, 0x3f317217, v32
	v_fma_f32 v34, v32, s96, -v34
	v_fmac_f32_e32 v34, 0x3377d1cf, v32
	v_fmac_f32_e32 v34, 0x3f317217, v32
	v_cmp_lt_f32_e64 s[38:39], |v32|, s58
	s_nop 1
	v_cndmask_b32_e64 v32, v32, v34, s[38:39]
	v_cndmask_b32_e32 v34, 0, v242, vcc
	v_sub_f32_e32 v32, v32, v34
	v_mul_f32_e32 v34, 0xbfb8aa3b, v155
	v_exp_f32_e32 v34, v34
	v_max_f32_e32 v32, 0xc2700000, v32
	v_add_f32_e32 v32, v32, v35
	v_add_f32_e32 v34, 1.0, v34
	v_rcp_f32_e32 v34, v34
	s_nop 0
	v_fma_f32 v34, v34, v27, v67
	v_cmp_gt_f32_e32 vcc, s37, v34
	s_nop 1
	v_cndmask_b32_e64 v36, 0, 32, vcc
	v_ldexp_f32 v34, v34, v36
	v_log_f32_e32 v34, v34
	s_nop 0
	v_mul_f32_e32 v36, 0x3f317217, v34
	v_fma_f32 v36, v34, s96, -v36
	v_fmac_f32_e32 v36, 0x3377d1cf, v34
	v_fmac_f32_e32 v36, 0x3f317217, v34
	v_cmp_lt_f32_e64 s[38:39], |v34|, s58
	s_nop 1
	v_cndmask_b32_e64 v34, v34, v36, s[38:39]
	v_cndmask_b32_e32 v36, 0, v242, vcc
	v_sub_f32_e32 v34, v34, v36
	v_max_f32_e32 v34, 0xc2700000, v34
	v_add_f32_e32 v37, v34, v32
	v_mul_f32_e32 v34, 0xbfb8aa3b, v156
	v_exp_f32_e32 v34, v34
	s_nop 0
	v_add_f32_e32 v34, 1.0, v34
	v_rcp_f32_e32 v34, v34
	s_nop 0
	v_fma_f32 v34, v34, v27, v67
	v_cmp_gt_f32_e32 vcc, s37, v34
	s_nop 1
	v_cndmask_b32_e64 v36, 0, 32, vcc
	v_ldexp_f32 v34, v34, v36
	v_log_f32_e32 v34, v34
	s_nop 0
	v_mul_f32_e32 v36, 0x3f317217, v34
	v_fma_f32 v36, v34, s96, -v36
	v_fmac_f32_e32 v36, 0x3377d1cf, v34
	v_fmac_f32_e32 v36, 0x3f317217, v34
	v_cmp_lt_f32_e64 s[38:39], |v34|, s58
	s_nop 1
	v_cndmask_b32_e64 v34, v34, v36, s[38:39]
	v_cndmask_b32_e32 v36, 0, v242, vcc
	v_sub_f32_e32 v34, v34, v36
	v_mul_f32_e32 v36, 0xbfb8aa3b, v157
	v_exp_f32_e32 v36, v36
	v_max_f32_e32 v34, 0xc2700000, v34
	v_add_f32_e32 v34, v34, v37
	v_add_f32_e32 v36, 1.0, v36
	v_rcp_f32_e32 v36, v36
	s_nop 0
	v_fma_f32 v36, v36, v27, v67
	v_cmp_gt_f32_e32 vcc, s37, v36
	s_nop 1
	v_cndmask_b32_e64 v38, 0, 32, vcc
	v_ldexp_f32 v36, v36, v38
	v_log_f32_e32 v36, v36
	s_nop 0
	v_mul_f32_e32 v38, 0x3f317217, v36
	v_fma_f32 v38, v36, s96, -v38
	v_fmac_f32_e32 v38, 0x3377d1cf, v36
	v_fmac_f32_e32 v38, 0x3f317217, v36
	v_cmp_lt_f32_e64 s[38:39], |v36|, s58
	s_nop 1
	v_cndmask_b32_e64 v36, v36, v38, s[38:39]
	v_cndmask_b32_e32 v38, 0, v242, vcc
	v_sub_f32_e32 v36, v36, v38
	v_max_f32_e32 v36, 0xc2700000, v36
	v_add_f32_e32 v39, v36, v34
	v_mul_f32_e32 v36, 0xbfb8aa3b, v158
	v_exp_f32_e32 v36, v36
	s_nop 0
	v_add_f32_e32 v36, 1.0, v36
	v_rcp_f32_e32 v36, v36
	s_nop 0
	v_fma_f32 v36, v36, v27, v67
	v_cmp_gt_f32_e32 vcc, s37, v36
	s_nop 1
	v_cndmask_b32_e64 v38, 0, 32, vcc
	v_ldexp_f32 v36, v36, v38
	v_log_f32_e32 v36, v36
	s_nop 0
	v_mul_f32_e32 v38, 0x3f317217, v36
	v_fma_f32 v38, v36, s96, -v38
	v_fmac_f32_e32 v38, 0x3377d1cf, v36
	v_fmac_f32_e32 v38, 0x3f317217, v36
	v_cmp_lt_f32_e64 s[38:39], |v36|, s58
	s_nop 1
	v_cndmask_b32_e64 v36, v36, v38, s[38:39]
	v_cndmask_b32_e32 v38, 0, v242, vcc
; #define LAS __attribute__((address_space(3)))
; __device__ __forceinline__ float bf2f(bf16_t b) { return __uint_as_float(((unsigned)b) << 16); }
; __device__ __forceinline__ float rcpf_(float x) { return __builtin_amdgcn_rcpf(x); }
; __device__ __forceinline__ void phase_hgrn_c3(const Params& p, int l, int bid, int nblk, LAS unsigned char* lds) {
;     ...
; #pragma unroll
;         for (int i = 0; i < 16; ++i) {
;             const float z = bf2f(fr_[i]);
;             const float sg1 = rcpf_(1.f + __expf(-z)), om = rcpf_(1.f + __expf(z));
;             const float f = lb + (1.f - lb) * sg1; run += fmaxf(__logf(f), -60.f); bl[i] = run; kk[i] = (1.f - lb) * om;
;         }
;         gsum[sg * 128 + k] = run;
; #pragma unroll
;         for (int i = 0; i < 4; ++i) { const int id = tid + 512 * i, vd = id >> 4, k8 = (id & 15) * 8; *(LAS u32x4*)(S0T + vd * 136 + k8) = s0v[i]; }
; #pragma unroll
;         for (int i = 0; i < 2; ++i) {
;             const int id = tid + 512 * i, s = id & 63, v8 = (id >> 6) * 8;
; #pragma unroll
;             for (int e = 0; e < 8; ++e) vT[(v8 + e) * 72 + s] = (bf16_t)vf_[i][e];
;         }
;         __syncthreads();
	v_sub_f32_e32 v36, v36, v38
	v_mul_f32_e32 v38, 0xbfb8aa3b, v159
	v_exp_f32_e32 v38, v38
	v_max_f32_e32 v36, 0xc2700000, v36
	v_add_f32_e32 v36, v36, v39
	v_add_f32_e32 v38, 1.0, v38
	v_rcp_f32_e32 v38, v38
	s_nop 0
	v_fma_f32 v38, v38, v27, v67
	v_cmp_gt_f32_e32 vcc, s37, v38
	s_nop 1
	v_cndmask_b32_e64 v40, 0, 32, vcc
	v_ldexp_f32 v38, v38, v40
	v_log_f32_e32 v38, v38
	s_nop 0
	v_mul_f32_e32 v40, 0x3f317217, v38
	v_fma_f32 v40, v38, s96, -v40
	v_fmac_f32_e32 v40, 0x3377d1cf, v38
	v_fmac_f32_e32 v40, 0x3f317217, v38
	v_cmp_lt_f32_e64 s[38:39], |v38|, s58
	s_nop 1
	v_cndmask_b32_e64 v38, v38, v40, s[38:39]
	v_cndmask_b32_e32 v40, 0, v242, vcc
	v_sub_f32_e32 v38, v38, v40
	v_max_f32_e32 v38, 0xc2700000, v38
	v_add_f32_e32 v41, v38, v36
	v_mul_f32_e32 v38, 0xbfb8aa3b, v160
	v_exp_f32_e32 v38, v38
	s_nop 0
	v_add_f32_e32 v38, 1.0, v38
	v_rcp_f32_e32 v38, v38
	s_nop 0
	v_fma_f32 v38, v38, v27, v67
	v_cmp_gt_f32_e32 vcc, s37, v38
	s_nop 1
	v_cndmask_b32_e64 v40, 0, 32, vcc
	v_ldexp_f32 v38, v38, v40
	v_log_f32_e32 v38, v38
	s_nop 0
	v_mul_f32_e32 v40, 0x3f317217, v38
	v_fma_f32 v40, v38, s96, -v40
	v_fmac_f32_e32 v40, 0x3377d1cf, v38
	v_fmac_f32_e32 v40, 0x3f317217, v38
	v_cmp_lt_f32_e64 s[38:39], |v38|, s58
	s_nop 1
	v_cndmask_b32_e64 v38, v38, v40, s[38:39]
	v_cndmask_b32_e32 v40, 0, v242, vcc
	v_sub_f32_e32 v38, v38, v40
	v_mul_f32_e32 v40, 0xbfb8aa3b, v161
	v_exp_f32_e32 v40, v40
	v_max_f32_e32 v38, 0xc2700000, v38
	v_add_f32_e32 v38, v38, v41
	v_add_f32_e32 v40, 1.0, v40
	v_rcp_f32_e32 v40, v40
	s_nop 0
	v_fma_f32 v40, v40, v27, v67
	v_cmp_gt_f32_e32 vcc, s37, v40
	s_nop 1
	v_cndmask_b32_e64 v63, 0, 32, vcc
	v_ldexp_f32 v40, v40, v63
	v_log_f32_e32 v40, v40
	s_nop 0
	v_mul_f32_e32 v63, 0x3f317217, v40
	v_fma_f32 v63, v40, s96, -v63
	v_fmac_f32_e32 v63, 0x3377d1cf, v40
	v_fmac_f32_e32 v63, 0x3f317217, v40
	v_cmp_lt_f32_e64 s[38:39], |v40|, s58
	s_nop 1
	v_cndmask_b32_e64 v40, v40, v63, s[38:39]
	v_cndmask_b32_e32 v63, 0, v242, vcc
	v_sub_f32_e32 v40, v40, v63
	v_max_f32_e32 v40, 0xc2700000, v40
	v_add_f32_e32 v63, v40, v38
	v_mul_f32_e32 v40, 0xbfb8aa3b, v162
	v_exp_f32_e32 v40, v40
	s_nop 0
	v_add_f32_e32 v40, 1.0, v40
	v_rcp_f32_e32 v40, v40
	s_nop 0
	v_fma_f32 v40, v40, v27, v67
	v_cmp_gt_f32_e32 vcc, s37, v40
	s_nop 1
	v_cndmask_b32_e64 v163, 0, 32, vcc
	v_ldexp_f32 v40, v40, v163
	v_log_f32_e32 v40, v40
	s_nop 0
	v_mul_f32_e32 v163, 0x3f317217, v40
	v_fma_f32 v163, v40, s96, -v163
	v_fmac_f32_e32 v163, 0x3377d1cf, v40
	v_fmac_f32_e32 v163, 0x3f317217, v40
	v_cmp_lt_f32_e64 s[38:39], |v40|, s58
	s_nop 1
	v_cndmask_b32_e64 v40, v40, v163, s[38:39]
	v_cndmask_b32_e32 v163, 0, v242, vcc
	v_sub_f32_e32 v40, v40, v163
	s_waitcnt vmcnt(42)
	v_lshlrev_b32_e32 v163, 16, v105
	v_mul_f32_e32 v164, 0xbfb8aa3b, v163
	v_exp_f32_e32 v164, v164
	v_max_f32_e32 v40, 0xc2700000, v40
	v_add_f32_e32 v40, v40, v63
	v_add_f32_e32 v164, 1.0, v164
	v_rcp_f32_e32 v164, v164
	s_nop 0
	v_fmac_f32_e32 v67, v164, v27
	v_cmp_gt_f32_e32 vcc, s37, v67
	s_nop 1
	v_cndmask_b32_e64 v164, 0, 32, vcc
	v_ldexp_f32 v67, v67, v164
	v_log_f32_e32 v67, v67
	s_nop 0
	v_mul_f32_e32 v164, 0x3f317217, v67
	v_fma_f32 v164, v67, s96, -v164
	v_fmac_f32_e32 v164, 0x3377d1cf, v67
	v_fmac_f32_e32 v164, 0x3f317217, v67
	v_cmp_lt_f32_e64 s[38:39], |v67|, s58
	s_nop 1
	v_cndmask_b32_e64 v67, v67, v164, s[38:39]
	v_cndmask_b32_e32 v164, 0, v242, vcc
	v_sub_f32_e32 v67, v67, v164
	v_max_f32_e32 v67, 0xc2700000, v67
	v_add_f32_e32 v67, v67, v40
	ds_write_b32 v95, v67
	s_waitcnt vmcnt(37)
	ds_write_b128 v119, v[0:3] offset:52224
	s_waitcnt vmcnt(36)
	ds_write_b128 v120, v[6:9] offset:52224
	s_waitcnt vmcnt(35)
	ds_write_b128 v121, v[10:13] offset:52224
	s_waitcnt vmcnt(34)
	ds_write_b128 v122, v[14:17] offset:52224
	s_waitcnt vmcnt(33)
	ds_write_b16 v123, v18
	ds_write_b16_d16_hi v123, v18 offset:144
	ds_write_b16 v123, v19 offset:288
	ds_write_b16_d16_hi v123, v19 offset:432
	ds_write_b16 v123, v20 offset:576
	ds_write_b16_d16_hi v123, v20 offset:720
	ds_write_b16 v123, v21 offset:864
	ds_write_b16_d16_hi v124, v21
	s_waitcnt vmcnt(32)
	ds_write_b16 v125, v22
	ds_write_b16_d16_hi v125, v22 offset:144
	ds_write_b16 v125, v23 offset:288
	ds_write_b16_d16_hi v125, v23 offset:432
	ds_write_b16 v125, v24 offset:576
	ds_write_b16_d16_hi v125, v24 offset:720
	ds_write_b16 v125, v25 offset:864
	ds_write_b16_d16_hi v126, v25
	s_waitcnt lgkmcnt(0)
	s_barrier
	s_and_saveexec_b64 s[38:39], s[6:7]
	s_cbranch_execz .LBB0_239
	ds_read_b32 v26, v98
	s_waitcnt lgkmcnt(0)
	v_add_f32_e32 v26, 0, v26
	s_or_b64 exec, exec, s[38:39]
	s_and_saveexec_b64 s[38:39], s[8:9]
	s_cbranch_execnz .LBB0_240

; #define LAS __attribute__((address_space(3)))
; __device__ __forceinline__ int tidx() { int t = (int)__builtin_amdgcn_workitem_id_x(); asm volatile("" : "+v"(t)); return t; }
; __device__ __forceinline__ int c1_job(int b, int k, int nblk) {
;     if (nblk != 256) { const int j = b + k * nblk; return j < NCHUNK * 8 ? j : -1; }
;     if (b >= 80 && b < 96) return -1;
;     if (b < 16) return k < 3 ? 2016 + 3 * b + k : -1;
;     const int r = (b < 80) ? b - 16 : b - 32;
;     if (k < 9) return r + 224 * k;
;     if (k == 9 && r < 48) return 2064 + r;
;     return -1;
; }
; __device__ __forceinline__ void phase_hgrn_c1(const Params& p, int l, int bid, int nblk, LAS unsigned char* lds) {
;     const int tid = tidx(), wid = tid >> 6, lane = tid & 63, k = tid & 127, sg = tid >> 7;
;     LAS bf16_t* kT = (LAS bf16_t*)lds;
;     LAS bf16_t* vT = (LAS bf16_t*)(lds + 18432);
;     LAS float* gsum = (LAS float*)(lds + 36864);
;     bf16_t fr_[16]; bf16x8 vf_[2];
;     int job = c1_job(bid, 0, nblk);
.LBB0_407:
	s_cmpk_eq_i32 s42, 0x100
	s_cselect_b64 s[16:17], -1, 0
	s_cmpk_lg_i32 s42, 0x100
	s_cselect_b64 s[4:5], -1, 0
	s_cmpk_lt_i32 s70, 0x840
	s_cselect_b64 s[6:7], -1, 0
	s_and_b32 s8, s70, -16
	s_cmpk_lg_i32 s8, 0x50
	s_cselect_b64 s[18:19], -1, 0
	s_cmpk_eq_i32 s8, 0x50
	s_cselect_b64 s[8:9], -1, 0
	s_cmp_gt_i32 s70, 15
	s_cselect_b64 s[20:21], -1, 0
	s_cmpk_lt_u32 s70, 0x50
	s_cselect_b32 s14, -16, 0xffffffe0
	s_mul_i32 s35, s70, 3
	s_add_i32 s14, s14, s70
	s_add_i32 s10, s35, 0x7e0
	s_or_b64 s[8:9], s[4:5], s[8:9]
	s_and_b64 s[4:5], s[4:5], s[6:7]
	s_and_b64 s[4:5], s[4:5], exec
	s_cselect_b32 s6, s70, -1
	s_cmp_lt_i32 s70, 16
	s_cselect_b32 s7, s10, s14
	s_and_b64 s[4:5], s[8:9], exec
	s_cselect_b32 s50, s6, s7
	s_waitcnt vmcnt(0)
	v_mov_b32_e32 v10, v234
	s_cmp_lt_i32 s50, 0
	s_waitcnt lgkmcnt(0)
	s_barrier
	s_cbranch_scc1 .LBB0_427
	s_add_i32 s4, s41, 7
	s_cmp_gt_u32 s4, 16
	s_load_dwordx2 s[26:27], s[0:1], 0x110
	s_cselect_b64 s[22:23], -1, 0
	s_cmp_lt_u32 s14, 48
	s_cselect_b64 s[24:25], -1, 0
	s_lshl_b32 s4, s50, 3
	v_ashrrev_i32_e32 v21, 7, v10
	s_and_b32 s6, s4, 0x7fffffc0
	s_lshl_b32 s4, s50, 7
	v_and_b32_e32 v26, 0x7f, v10
	s_and_b32 s7, s4, 0x380
	v_lshlrev_b32_e32 v27, 4, v21
	v_or_b32_e32 v2, s7, v26
	v_add_u32_e32 v11, s6, v27
	s_waitcnt lgkmcnt(0)
; __device__ __forceinline__ void phase_hgrn_c1(const Params& p, int l, int bid, int nblk, LAS unsigned char* lds) {
;     ...
;     int job = c1_job(bid, 0, nblk);
;     if (job >= 0) {
;         const int c = job >> 3, h = job & 7, r0 = c * 64, ch = h * 128 + k;
; #pragma unroll
;         for (int i = 0; i < 16; ++i) fr_[i] = p.P[(size_t)(r0 + 16 * sg + i) * NIN + C_FC + ch];
; #pragma unroll
;         for (int i = 0; i < 2; ++i) { const int id = tid + 512 * i, s = id & 63, v8 = (id >> 6) * 8; vf_[i] = *(const bf16x8*)(p.P + (size_t)(r0 + s) * NIN + C_IC + h * 128 + v8); }
;     }
	v_mov_b64_e32 v[0:1], s[26:27]
	v_mad_i64_i32 v[0:1], s[4:5], v11, s43, v[0:1]
	v_lshlrev_b32_e32 v4, 1, v2
	v_lshl_add_u64 v[0:1], v[0:1], 0, v[4:5]
	s_movk_i32 s8, 0x2000
	v_or_b32_e32 v6, 1, v11
	v_mov_b64_e32 v[2:3], s[26:27]
	v_add_co_u32_e32 v0, vcc, s8, v0
	v_mad_i64_i32 v[2:3], s[4:5], v6, s43, v[2:3]
	s_nop 0
	v_addc_co_u32_e32 v1, vcc, 0, v1, vcc
	v_lshl_add_u64 v[2:3], v[2:3], 0, v[4:5]
	v_or_b32_e32 v8, 2, v11
	v_mov_b64_e32 v[6:7], s[26:27]
	v_add_co_u32_e32 v2, vcc, s8, v2
	v_mad_i64_i32 v[6:7], s[4:5], v8, s43, v[6:7]
	s_nop 0
	v_addc_co_u32_e32 v3, vcc, 0, v3, vcc
	v_lshl_add_u64 v[6:7], v[6:7], 0, v[4:5]
	v_or_b32_e32 v12, 3, v11
	v_mov_b64_e32 v[8:9], s[26:27]
	v_add_co_u32_e32 v6, vcc, s8, v6
	v_mad_i64_i32 v[8:9], s[4:5], v12, s43, v[8:9]
	s_nop 0
	v_addc_co_u32_e32 v7, vcc, 0, v7, vcc
	v_lshl_add_u64 v[8:9], v[8:9], 0, v[4:5]
	v_or_b32_e32 v14, 4, v11
	v_mov_b64_e32 v[12:13], s[26:27]
	v_add_co_u32_e32 v8, vcc, s8, v8
	v_mad_i64_i32 v[12:13], s[4:5], v14, s43, v[12:13]
	s_nop 0
	v_addc_co_u32_e32 v9, vcc, 0, v9, vcc
	v_lshl_add_u64 v[12:13], v[12:13], 0, v[4:5]
	v_or_b32_e32 v16, 5, v11
	v_mov_b64_e32 v[14:15], s[26:27]
	v_add_co_u32_e32 v12, vcc, s8, v12
	v_mad_i64_i32 v[14:15], s[4:5], v16, s43, v[14:15]
	s_nop 0
	v_addc_co_u32_e32 v13, vcc, 0, v13, vcc
	v_lshl_add_u64 v[14:15], v[14:15], 0, v[4:5]
	v_or_b32_e32 v18, 6, v11
	v_mov_b64_e32 v[16:17], s[26:27]
	v_add_co_u32_e32 v14, vcc, s8, v14
	v_mad_i64_i32 v[16:17], s[4:5], v18, s43, v[16:17]
	s_nop 0
	v_addc_co_u32_e32 v15, vcc, 0, v15, vcc
	v_lshl_add_u64 v[16:17], v[16:17], 0, v[4:5]
	v_or_b32_e32 v20, 7, v11
	v_mov_b64_e32 v[18:19], s[26:27]
	v_add_co_u32_e32 v16, vcc, s8, v16
	v_mad_i64_i32 v[18:19], s[4:5], v20, s43, v[18:19]
	s_nop 0
	v_addc_co_u32_e32 v17, vcc, 0, v17, vcc
	v_lshl_add_u64 v[18:19], v[18:19], 0, v[4:5]
	v_add_co_u32_e32 v18, vcc, s8, v18
	v_and_b32_e32 v34, 63, v10
	s_nop 0
	v_addc_co_u32_e32 v19, vcc, 0, v19, vcc
	global_load_ushort v28, v[0:1], off offset:2048
	global_load_ushort v29, v[2:3], off offset:2048
	global_load_ushort v30, v[6:7], off offset:2048
	global_load_ushort v31, v[8:9], off offset:2048
	global_load_ushort v32, v[12:13], off offset:2048
	global_load_ushort v33, v[14:15], off offset:2048
	global_load_ushort v35, v[16:17], off offset:2048
	global_load_ushort v38, v[18:19], off offset:2048
	v_or_b32_e32 v2, 8, v11
	v_mov_b64_e32 v[0:1], s[26:27]
	v_mad_i64_i32 v[0:1], s[4:5], v2, s43, v[0:1]
	v_lshl_add_u64 v[0:1], v[0:1], 0, v[4:5]
	v_or_b32_e32 v6, 9, v11
	v_mov_b64_e32 v[2:3], s[26:27]
	v_add_co_u32_e32 v0, vcc, s8, v0
	v_mad_i64_i32 v[2:3], s[4:5], v6, s43, v[2:3]
	s_nop 0
	v_addc_co_u32_e32 v1, vcc, 0, v1, vcc
	v_lshl_add_u64 v[2:3], v[2:3], 0, v[4:5]
	v_or_b32_e32 v8, 10, v11
	v_mov_b64_e32 v[6:7], s[26:27]
	v_add_co_u32_e32 v2, vcc, s8, v2
	v_mad_i64_i32 v[6:7], s[4:5], v8, s43, v[6:7]
	s_nop 0
	v_addc_co_u32_e32 v3, vcc, 0, v3, vcc
	v_lshl_add_u64 v[6:7], v[6:7], 0, v[4:5]
	v_or_b32_e32 v12, 11, v11
	v_mov_b64_e32 v[8:9], s[26:27]
	v_add_co_u32_e32 v6, vcc, s8, v6
	v_mad_i64_i32 v[8:9], s[4:5], v12, s43, v[8:9]
	s_nop 0
	v_addc_co_u32_e32 v7, vcc, 0, v7, vcc
	v_lshl_add_u64 v[8:9], v[8:9], 0, v[4:5]
	v_or_b32_e32 v14, 12, v11
	v_mov_b64_e32 v[12:13], s[26:27]
	v_add_co_u32_e32 v8, vcc, s8, v8
	v_mad_i64_i32 v[12:13], s[4:5], v14, s43, v[12:13]
	s_nop 0
	v_addc_co_u32_e32 v9, vcc, 0, v9, vcc
	v_lshl_add_u64 v[12:13], v[12:13], 0, v[4:5]
	v_or_b32_e32 v16, 13, v11
	v_mov_b64_e32 v[14:15], s[26:27]
	v_add_co_u32_e32 v12, vcc, s8, v12
	v_mad_i64_i32 v[14:15], s[4:5], v16, s43, v[14:15]
	s_nop 0
	v_addc_co_u32_e32 v13, vcc, 0, v13, vcc
	v_lshl_add_u64 v[14:15], v[14:15], 0, v[4:5]
	v_or_b32_e32 v18, 14, v11
	v_mov_b64_e32 v[16:17], s[26:27]
	v_add_co_u32_e32 v14, vcc, s8, v14
	v_mad_i64_i32 v[16:17], s[4:5], v18, s43, v[16:17]
	s_nop 0
	v_addc_co_u32_e32 v15, vcc, 0, v15, vcc
	v_lshl_add_u64 v[16:17], v[16:17], 0, v[4:5]
	v_or_b32_e32 v11, 15, v11
	v_mov_b64_e32 v[18:19], s[26:27]
	v_add_co_u32_e32 v16, vcc, s8, v16
	v_mad_i64_i32 v[18:19], s[4:5], v11, s43, v[18:19]
	s_nop 0
	v_addc_co_u32_e32 v17, vcc, 0, v17, vcc
	v_lshl_add_u64 v[18:19], v[18:19], 0, v[4:5]
	v_add_co_u32_e32 v18, vcc, s8, v18
	v_add_u32_e32 v4, 0x200, v10
	s_nop 0
	v_addc_co_u32_e32 v19, vcc, 0, v19, vcc
	global_load_ushort v44, v[0:1], off offset:2048
	global_load_ushort v45, v[2:3], off offset:2048
	global_load_ushort v46, v[6:7], off offset:2048
	global_load_ushort v47, v[8:9], off offset:2048
	global_load_ushort v48, v[12:13], off offset:2048
	global_load_ushort v49, v[14:15], off offset:2048
	global_load_ushort v50, v[16:17], off offset:2048
	global_load_ushort v51, v[18:19], off offset:2048
	v_or_b32_e32 v2, s6, v34
	v_mov_b64_e32 v[0:1], s[26:27]
	v_mad_u64_u32 v[0:1], s[4:5], v2, s43, v[0:1]
	s_lshl_b32 s4, s7, 1
	s_mov_b32 s5, s51
	v_ashrrev_i32_e32 v23, 3, v10
	v_ashrrev_i32_e32 v24, 3, v4
	v_lshl_add_u64 v[0:1], v[0:1], 0, s[4:5]
	v_and_b32_e32 v12, -8, v23
	v_and_b32_e32 v14, -8, v24
	v_lshl_add_u64 v[0:1], v[0:1], 0, s[62:63]
	v_ashrrev_i32_e32 v13, 31, v12
	v_ashrrev_i32_e32 v15, 31, v14
	v_lshl_add_u64 v[2:3], v[12:13], 1, v[0:1]
	v_lshl_add_u64 v[6:7], v[14:15], 1, v[0:1]
	global_load_dwordx4 v[0:3], v[2:3], off
	s_nop 0
	global_load_dwordx4 v[6:9], v[6:7], off
	v_ashrrev_i32_e32 v4, 2, v10
	v_and_b32_e32 v16, -16, v4
	v_bfi_b32 v17, -16, v4, v10
	v_and_b32_e32 v4, 48, v10
	v_add_u32_e32 v4, 0, v4
	s_movk_i32 s8, 0x90
	v_mad_u64_u32 v[18:19], s[6:7], v17, s8, v[4:5]
	v_lshl_add_u32 v37, v26, 2, 0
	s_movk_i32 s4, 0x8c
	v_and_b32_e32 v39, 15, v10
	v_lshlrev_b32_e32 v17, 7, v10
	v_lshrrev_b32_e32 v19, 2, v10
	v_or_b32_e32 v23, 7, v23
	v_or_b32_e32 v24, 7, v24
	v_lshl_add_u32 v25, v34, 1, 0
	v_mad_u32_u24 v42, v26, s4, v37
	v_lshlrev_b32_e32 v43, 5, v21
	s_movk_i32 s4, 0x80
	v_and_b32_e32 v20, 0x780, v17
	v_and_b32_e32 v22, 12, v19
	v_mul_lo_u32 v19, v12, s8
	v_mul_lo_u32 v23, v23, s8
	v_mul_lo_u32 v40, v14, s8
	v_mul_lo_u32 v24, v24, s8
	v_cmp_lt_i32_e64 s[6:7], 0, v21
	v_cmp_lt_i32_e64 s[8:9], 1, v21
	v_cmp_lt_i32_e64 s[10:11], 2, v21
	v_cmp_lt_i32_e64 s[12:13], 3, v21
	v_mul_u32_u24_e32 v21, 0x90, v39
	s_movk_i32 s59, 0x2000
	s_add_i32 s31, s14, 0x810
	s_mov_b32 s34, 0
	v_lshl_add_u32 v36, v10, 2, 0
	v_cmp_gt_u32_e64 s[4:5], s4, v10
	v_mov_b32_e32 v11, v5
	v_ashrrev_i32_e32 v17, 31, v16
	s_addk_i32 s35, 0x7e1
	s_add_i32 s38, s14, 0xe0
	s_add_i32 s39, s42, s70
	v_add_u32_e32 v19, v25, v19
	v_add_u32_e32 v39, v25, v23
	v_add_u32_e32 v40, v25, v40
	v_add_u32_e32 v41, v25, v24
	v_add_u32_e32 v42, v42, v43
	v_add_u32_e32 v43, v4, v21
	v_lshlrev_b32_e32 v4, 2, v22
	v_lshlrev_b32_e32 v20, 2, v20
	s_waitcnt vmcnt(0)
	s_branch .LBB0_410

; __device__ __forceinline__ float bf2f(bf16_t b) { return __uint_as_float(((unsigned)b) << 16); }
; __device__ __forceinline__ float rcpf_(float x) { return __builtin_amdgcn_rcpf(x); }
; __device__ __forceinline__ void phase_hgrn_c1(const Params& p, int l, int bid, int nblk, LAS unsigned char* lds) {
;     ...
;         const float lb = hgrn_lb(p, l, ch);
;         float bl[16], kk[16]; float run = 0.f;
; #pragma unroll
;         for (int i = 0; i < 16; ++i) {
;             const float z = bf2f(fr_[i]);
;             const float sg1 = rcpf_(1.f + __expf(-z)), om = rcpf_(1.f + __expf(z));
;             const float f = lb + (1.f - lb) * sg1; run += fmaxf(__logf(f), -60.f); bl[i] = run; kk[i] = (1.f - lb) * om;
;         }
.LBB0_412:
	s_waitcnt vmcnt(25)
	v_lshlrev_b32_e32 v25, 16, v28
	v_mul_f32_e32 v21, 0xbfb8aa3b, v25
	v_exp_f32_e32 v21, v21
	v_sub_f32_e32 v22, 1.0, v65
	s_waitcnt vmcnt(24)
	v_lshlrev_b32_e32 v55, 16, v29
	s_waitcnt vmcnt(23)
	v_lshlrev_b32_e32 v57, 16, v30
	v_add_f32_e32 v21, 1.0, v21
	v_rcp_f32_e32 v21, v21
	s_waitcnt vmcnt(22)
	v_lshlrev_b32_e32 v59, 16, v31
	s_waitcnt vmcnt(21)
	v_lshlrev_b32_e32 v61, 16, v32
	s_waitcnt vmcnt(20)
	v_lshlrev_b32_e32 v63, 16, v33
	v_fma_f32 v21, v21, v22, v65
	v_cmp_gt_f32_e32 vcc, s37, v21
	s_waitcnt vmcnt(19)
	v_lshlrev_b32_e32 v66, 16, v35
	s_waitcnt vmcnt(18)
	v_lshlrev_b32_e32 v68, 16, v38
	v_cndmask_b32_e64 v23, 0, 32, vcc
	v_ldexp_f32 v21, v21, v23
	v_log_f32_e32 v21, v21
	s_waitcnt vmcnt(17)
	v_lshlrev_b32_e32 v70, 16, v44
	s_waitcnt vmcnt(16)
	v_lshlrev_b32_e32 v72, 16, v45
	s_waitcnt vmcnt(15)
	v_lshlrev_b32_e32 v74, 16, v46
	v_mul_f32_e32 v23, 0x3f317217, v21
	v_fma_f32 v23, v21, s96, -v23
	v_fmac_f32_e32 v23, 0x3377d1cf, v21
	v_fmac_f32_e32 v23, 0x3f317217, v21
	v_cmp_lt_f32_e64 s[14:15], |v21|, s58
	s_waitcnt vmcnt(14)
	v_lshlrev_b32_e32 v75, 16, v47
	s_waitcnt vmcnt(13)
	v_lshlrev_b32_e32 v76, 16, v48
	v_cndmask_b32_e64 v21, v21, v23, s[14:15]
	v_cndmask_b32_e32 v23, 0, v242, vcc
	v_sub_f32_e32 v21, v21, v23
	v_mul_f32_e32 v23, 0xbfb8aa3b, v55
	v_exp_f32_e32 v23, v23
	v_max_f32_e32 v21, 0xc2700000, v21
	v_add_f32_e32 v21, 0, v21
	s_waitcnt vmcnt(12)
	v_lshlrev_b32_e32 v77, 16, v49
	v_add_f32_e32 v23, 1.0, v23
	v_rcp_f32_e32 v23, v23
	s_waitcnt vmcnt(11)
	v_lshlrev_b32_e32 v78, 16, v50
	v_fma_f32 v23, v23, v22, v65
	v_cmp_gt_f32_e32 vcc, s37, v23
	s_nop 1
	v_cndmask_b32_e64 v24, 0, 32, vcc
	v_ldexp_f32 v23, v23, v24
	v_log_f32_e32 v23, v23
	s_nop 0
	v_mul_f32_e32 v24, 0x3f317217, v23
	v_fma_f32 v24, v23, s96, -v24
	v_fmac_f32_e32 v24, 0x3377d1cf, v23
	v_fmac_f32_e32 v24, 0x3f317217, v23
	v_cmp_lt_f32_e64 s[14:15], |v23|, s58
	s_nop 1
	v_cndmask_b32_e64 v23, v23, v24, s[14:15]
	v_cndmask_b32_e32 v24, 0, v242, vcc
	v_sub_f32_e32 v23, v23, v24
	v_max_f32_e32 v23, 0xc2700000, v23
	v_add_f32_e32 v24, v23, v21
	v_mul_f32_e32 v23, 0xbfb8aa3b, v57
	v_exp_f32_e32 v23, v23
	s_nop 0
	v_add_f32_e32 v23, 1.0, v23
	v_rcp_f32_e32 v23, v23
	s_nop 0
	v_fma_f32 v23, v23, v22, v65
	v_cmp_gt_f32_e32 vcc, s37, v23
	s_nop 1
	v_cndmask_b32_e64 v52, 0, 32, vcc
	v_ldexp_f32 v23, v23, v52
	v_log_f32_e32 v23, v23
	s_nop 0
	v_mul_f32_e32 v52, 0x3f317217, v23
	v_fma_f32 v52, v23, s96, -v52
	v_fmac_f32_e32 v52, 0x3377d1cf, v23
	v_fmac_f32_e32 v52, 0x3f317217, v23
	v_cmp_lt_f32_e64 s[14:15], |v23|, s58
	s_nop 1
	v_cndmask_b32_e64 v23, v23, v52, s[14:15]
	v_cndmask_b32_e32 v52, 0, v242, vcc
	v_sub_f32_e32 v23, v23, v52
	v_max_f32_e32 v23, 0xc2700000, v23
	v_add_f32_e32 v52, v23, v24
	v_mul_f32_e32 v23, 0xbfb8aa3b, v59
	v_exp_f32_e32 v23, v23
	s_nop 0
	v_add_f32_e32 v23, 1.0, v23
	v_rcp_f32_e32 v23, v23
	s_nop 0
	v_fma_f32 v23, v23, v22, v65
	v_cmp_gt_f32_e32 vcc, s37, v23
	s_nop 1
	v_cndmask_b32_e64 v53, 0, 32, vcc
	v_ldexp_f32 v23, v23, v53
	v_log_f32_e32 v23, v23
	s_nop 0
	v_mul_f32_e32 v53, 0x3f317217, v23
	v_fma_f32 v53, v23, s96, -v53
	v_fmac_f32_e32 v53, 0x3377d1cf, v23
	v_fmac_f32_e32 v53, 0x3f317217, v23
	v_cmp_lt_f32_e64 s[14:15], |v23|, s58
	s_nop 1
	v_cndmask_b32_e64 v23, v23, v53, s[14:15]
	v_cndmask_b32_e32 v53, 0, v242, vcc
	v_sub_f32_e32 v23, v23, v53
	v_mul_f32_e32 v53, 0xbfb8aa3b, v61
	v_exp_f32_e32 v53, v53
	v_max_f32_e32 v23, 0xc2700000, v23
	v_add_f32_e32 v23, v23, v52
	v_add_f32_e32 v53, 1.0, v53
	v_rcp_f32_e32 v53, v53
	s_nop 0
	v_fma_f32 v53, v53, v22, v65
	v_cmp_gt_f32_e32 vcc, s37, v53
	s_nop 1
	v_cndmask_b32_e64 v54, 0, 32, vcc
	v_ldexp_f32 v53, v53, v54
	v_log_f32_e32 v53, v53
	s_nop 0
	v_mul_f32_e32 v54, 0x3f317217, v53
	v_fma_f32 v54, v53, s96, -v54
	v_fmac_f32_e32 v54, 0x3377d1cf, v53
	v_fmac_f32_e32 v54, 0x3f317217, v53
	v_cmp_lt_f32_e64 s[14:15], |v53|, s58
	s_nop 1
	v_cndmask_b32_e64 v53, v53, v54, s[14:15]
	v_cndmask_b32_e32 v54, 0, v242, vcc
	v_sub_f32_e32 v53, v53, v54
	v_mul_f32_e32 v54, 0xbfb8aa3b, v63
	v_exp_f32_e32 v54, v54
	v_max_f32_e32 v53, 0xc2700000, v53
	v_add_f32_e32 v53, v53, v23
	v_add_f32_e32 v54, 1.0, v54
	v_rcp_f32_e32 v54, v54
	s_nop 0
	v_fma_f32 v54, v54, v22, v65
	v_cmp_gt_f32_e32 vcc, s37, v54
	s_nop 1
	v_cndmask_b32_e64 v56, 0, 32, vcc
	v_ldexp_f32 v54, v54, v56
	v_log_f32_e32 v54, v54
	s_nop 0
	v_mul_f32_e32 v56, 0x3f317217, v54
	v_fma_f32 v56, v54, s96, -v56
	v_fmac_f32_e32 v56, 0x3377d1cf, v54
	v_fmac_f32_e32 v56, 0x3f317217, v54
	v_cmp_lt_f32_e64 s[14:15], |v54|, s58
	s_nop 1
	v_cndmask_b32_e64 v54, v54, v56, s[14:15]
	v_cndmask_b32_e32 v56, 0, v242, vcc
	v_sub_f32_e32 v54, v54, v56
	v_mul_f32_e32 v56, 0xbfb8aa3b, v66
	v_exp_f32_e32 v56, v56
	v_max_f32_e32 v54, 0xc2700000, v54
	v_add_f32_e32 v54, v54, v53
	v_add_f32_e32 v56, 1.0, v56
	v_rcp_f32_e32 v56, v56
	s_nop 0
	v_fma_f32 v56, v56, v22, v65
	v_cmp_gt_f32_e32 vcc, s37, v56
	s_nop 1
	v_cndmask_b32_e64 v58, 0, 32, vcc
	v_ldexp_f32 v56, v56, v58
	v_log_f32_e32 v56, v56
	s_nop 0
	v_mul_f32_e32 v58, 0x3f317217, v56
	v_fma_f32 v58, v56, s96, -v58
	v_fmac_f32_e32 v58, 0x3377d1cf, v56
	v_fmac_f32_e32 v58, 0x3f317217, v56
	v_cmp_lt_f32_e64 s[14:15], |v56|, s58
	s_nop 1
	v_cndmask_b32_e64 v56, v56, v58, s[14:15]
	v_cndmask_b32_e32 v58, 0, v242, vcc
	v_sub_f32_e32 v56, v56, v58
	v_mul_f32_e32 v58, 0xbfb8aa3b, v68
	v_exp_f32_e32 v58, v58
	v_max_f32_e32 v56, 0xc2700000, v56
	v_add_f32_e32 v56, v56, v54
	v_add_f32_e32 v58, 1.0, v58
	v_rcp_f32_e32 v58, v58
	s_nop 0
	v_fma_f32 v58, v58, v22, v65
	v_cmp_gt_f32_e32 vcc, s37, v58
	s_nop 1
	v_cndmask_b32_e64 v60, 0, 32, vcc
	v_ldexp_f32 v58, v58, v60
	v_log_f32_e32 v58, v58
; __device__ __forceinline__ float bf2f(bf16_t b) { return __uint_as_float(((unsigned)b) << 16); }
; __device__ __forceinline__ float rcpf_(float x) { return __builtin_amdgcn_rcpf(x); }
; __device__ __forceinline__ void phase_hgrn_c1(const Params& p, int l, int bid, int nblk, LAS unsigned char* lds) {
;     ...
;         const float lb = hgrn_lb(p, l, ch);
;         float bl[16], kk[16]; float run = 0.f;
; #pragma unroll
;         for (int i = 0; i < 16; ++i) {
;             const float z = bf2f(fr_[i]);
;             const float sg1 = rcpf_(1.f + __expf(-z)), om = rcpf_(1.f + __expf(z));
;             const float f = lb + (1.f - lb) * sg1; run += fmaxf(__logf(f), -60.f); bl[i] = run; kk[i] = (1.f - lb) * om;
;         }
;         gsum[sg * 128 + k] = run;
; #pragma unroll
;         for (int i = 0; i < 2; ++i) {
;             const int id = tid + 512 * i, s = id & 63, v8 = (id >> 6) * 8;
; #pragma unroll
;             for (int e = 0; e < 8; ++e) vT[(v8 + e) * 72 + s] = (bf16_t)vf_[i][e];
;         }
;         const int njob = c1_job(bid, kj + 1, nblk);
	s_nop 0
	v_mul_f32_e32 v60, 0x3f317217, v58
	v_fma_f32 v60, v58, s96, -v60
	v_fmac_f32_e32 v60, 0x3377d1cf, v58
	v_fmac_f32_e32 v60, 0x3f317217, v58
	v_cmp_lt_f32_e64 s[14:15], |v58|, s58
	s_nop 1
	v_cndmask_b32_e64 v58, v58, v60, s[14:15]
	v_cndmask_b32_e32 v60, 0, v242, vcc
	v_sub_f32_e32 v58, v58, v60
	v_mul_f32_e32 v60, 0xbfb8aa3b, v70
	v_exp_f32_e32 v60, v60
	v_max_f32_e32 v58, 0xc2700000, v58
	v_add_f32_e32 v58, v58, v56
	v_add_f32_e32 v60, 1.0, v60
	v_rcp_f32_e32 v60, v60
	s_nop 0
	v_fma_f32 v60, v60, v22, v65
	v_cmp_gt_f32_e32 vcc, s37, v60
	s_nop 1
	v_cndmask_b32_e64 v62, 0, 32, vcc
	v_ldexp_f32 v60, v60, v62
	v_log_f32_e32 v60, v60
	s_nop 0
	v_mul_f32_e32 v62, 0x3f317217, v60
	v_fma_f32 v62, v60, s96, -v62
	v_fmac_f32_e32 v62, 0x3377d1cf, v60
	v_fmac_f32_e32 v62, 0x3f317217, v60
	v_cmp_lt_f32_e64 s[14:15], |v60|, s58
	s_nop 1
	v_cndmask_b32_e64 v60, v60, v62, s[14:15]
	v_cndmask_b32_e32 v62, 0, v242, vcc
	v_sub_f32_e32 v60, v60, v62
	v_mul_f32_e32 v62, 0xbfb8aa3b, v72
	v_exp_f32_e32 v62, v62
	v_max_f32_e32 v60, 0xc2700000, v60
	v_add_f32_e32 v60, v60, v58
	v_add_f32_e32 v62, 1.0, v62
	v_rcp_f32_e32 v62, v62
	s_nop 0
	v_fma_f32 v62, v62, v22, v65
	v_cmp_gt_f32_e32 vcc, s37, v62
	s_nop 1
	v_cndmask_b32_e64 v64, 0, 32, vcc
	v_ldexp_f32 v62, v62, v64
	v_log_f32_e32 v62, v62
	s_nop 0
	v_mul_f32_e32 v64, 0x3f317217, v62
	v_fma_f32 v64, v62, s96, -v64
	v_fmac_f32_e32 v64, 0x3377d1cf, v62
	v_fmac_f32_e32 v64, 0x3f317217, v62
	v_cmp_lt_f32_e64 s[14:15], |v62|, s58
	s_nop 1
	v_cndmask_b32_e64 v62, v62, v64, s[14:15]
	v_cndmask_b32_e32 v64, 0, v242, vcc
	v_sub_f32_e32 v62, v62, v64
	v_mul_f32_e32 v64, 0xbfb8aa3b, v74
	v_exp_f32_e32 v64, v64
	v_max_f32_e32 v62, 0xc2700000, v62
	v_add_f32_e32 v62, v62, v60
	v_add_f32_e32 v64, 1.0, v64
	v_rcp_f32_e32 v64, v64
	s_nop 0
	v_fma_f32 v64, v64, v22, v65
	v_cmp_gt_f32_e32 vcc, s37, v64
	s_nop 1
	v_cndmask_b32_e64 v67, 0, 32, vcc
	v_ldexp_f32 v64, v64, v67
	v_log_f32_e32 v64, v64
	s_nop 0
	v_mul_f32_e32 v67, 0x3f317217, v64
	v_fma_f32 v67, v64, s96, -v67
	v_fmac_f32_e32 v67, 0x3377d1cf, v64
	v_fmac_f32_e32 v67, 0x3f317217, v64
	v_cmp_lt_f32_e64 s[14:15], |v64|, s58
	s_nop 1
	v_cndmask_b32_e64 v64, v64, v67, s[14:15]
	v_cndmask_b32_e32 v67, 0, v242, vcc
	v_sub_f32_e32 v64, v64, v67
	v_mul_f32_e32 v67, 0xbfb8aa3b, v75
	v_exp_f32_e32 v67, v67
	v_max_f32_e32 v64, 0xc2700000, v64
	v_add_f32_e32 v64, v64, v62
	v_add_f32_e32 v67, 1.0, v67
	v_rcp_f32_e32 v67, v67
	s_nop 0
	v_fma_f32 v67, v67, v22, v65
	v_cmp_gt_f32_e32 vcc, s37, v67
	s_nop 1
	v_cndmask_b32_e64 v69, 0, 32, vcc
	v_ldexp_f32 v67, v67, v69
	v_log_f32_e32 v67, v67
	s_nop 0
	v_mul_f32_e32 v69, 0x3f317217, v67
	v_fma_f32 v69, v67, s96, -v69
	v_fmac_f32_e32 v69, 0x3377d1cf, v67
	v_fmac_f32_e32 v69, 0x3f317217, v67
	v_cmp_lt_f32_e64 s[14:15], |v67|, s58
	s_nop 1
	v_cndmask_b32_e64 v67, v67, v69, s[14:15]
	v_cndmask_b32_e32 v69, 0, v242, vcc
	v_sub_f32_e32 v67, v67, v69
	v_mul_f32_e32 v69, 0xbfb8aa3b, v76
	v_exp_f32_e32 v69, v69
	v_max_f32_e32 v67, 0xc2700000, v67
	v_add_f32_e32 v67, v67, v64
	v_add_f32_e32 v69, 1.0, v69
	v_rcp_f32_e32 v69, v69
	s_nop 0
	v_fma_f32 v69, v69, v22, v65
	v_cmp_gt_f32_e32 vcc, s37, v69
	s_nop 1
	v_cndmask_b32_e64 v71, 0, 32, vcc
	v_ldexp_f32 v69, v69, v71
	v_log_f32_e32 v69, v69
	s_nop 0
	v_mul_f32_e32 v71, 0x3f317217, v69
	v_fma_f32 v71, v69, s96, -v71
	v_fmac_f32_e32 v71, 0x3377d1cf, v69
	v_fmac_f32_e32 v71, 0x3f317217, v69
	v_cmp_lt_f32_e64 s[14:15], |v69|, s58
	s_nop 1
	v_cndmask_b32_e64 v69, v69, v71, s[14:15]
	v_cndmask_b32_e32 v71, 0, v242, vcc
	v_sub_f32_e32 v69, v69, v71
	v_mul_f32_e32 v71, 0xbfb8aa3b, v77
	v_exp_f32_e32 v71, v71
	v_max_f32_e32 v69, 0xc2700000, v69
	v_add_f32_e32 v69, v69, v67
	v_add_f32_e32 v71, 1.0, v71
	v_rcp_f32_e32 v71, v71
	s_nop 0
	v_fma_f32 v71, v71, v22, v65
	v_cmp_gt_f32_e32 vcc, s37, v71
	s_nop 1
	v_cndmask_b32_e64 v73, 0, 32, vcc
	v_ldexp_f32 v71, v71, v73
	v_log_f32_e32 v71, v71
	s_nop 0
	v_mul_f32_e32 v73, 0x3f317217, v71
	v_fma_f32 v73, v71, s96, -v73
	v_fmac_f32_e32 v73, 0x3377d1cf, v71
	v_fmac_f32_e32 v73, 0x3f317217, v71
	v_cmp_lt_f32_e64 s[14:15], |v71|, s58
	s_nop 1
	v_cndmask_b32_e64 v71, v71, v73, s[14:15]
	v_cndmask_b32_e32 v73, 0, v242, vcc
	v_sub_f32_e32 v71, v71, v73
	v_mul_f32_e32 v73, 0xbfb8aa3b, v78
	v_exp_f32_e32 v73, v73
	v_max_f32_e32 v71, 0xc2700000, v71
	v_add_f32_e32 v71, v71, v69
	v_add_f32_e32 v73, 1.0, v73
	v_rcp_f32_e32 v73, v73
	s_nop 0
	v_fma_f32 v73, v73, v22, v65
	v_cmp_gt_f32_e32 vcc, s37, v73
	s_nop 1
	v_cndmask_b32_e64 v79, 0, 32, vcc
	v_ldexp_f32 v73, v73, v79
	v_log_f32_e32 v73, v73
	s_nop 0
	v_mul_f32_e32 v79, 0x3f317217, v73
	v_fma_f32 v79, v73, s96, -v79
	v_fmac_f32_e32 v79, 0x3377d1cf, v73
	v_fmac_f32_e32 v79, 0x3f317217, v73
	v_cmp_lt_f32_e64 s[14:15], |v73|, s58
	s_nop 1
	v_cndmask_b32_e64 v73, v73, v79, s[14:15]
	v_cndmask_b32_e32 v79, 0, v242, vcc
	v_sub_f32_e32 v73, v73, v79
	s_waitcnt vmcnt(10)
	v_lshlrev_b32_e32 v79, 16, v51
	v_mul_f32_e32 v80, 0xbfb8aa3b, v79
	v_exp_f32_e32 v80, v80
	v_max_f32_e32 v73, 0xc2700000, v73
	v_add_f32_e32 v73, v73, v71
	v_add_f32_e32 v80, 1.0, v80
	v_rcp_f32_e32 v80, v80
	s_nop 0
	v_fmac_f32_e32 v65, v80, v22
	v_cmp_gt_f32_e32 vcc, s37, v65
	s_nop 1
	v_cndmask_b32_e64 v80, 0, 32, vcc
	v_ldexp_f32 v65, v65, v80
	v_log_f32_e32 v65, v65
	s_nop 0
	v_mul_f32_e32 v80, 0x3f317217, v65
	v_fma_f32 v80, v65, s96, -v80
	v_fmac_f32_e32 v80, 0x3377d1cf, v65
	v_fmac_f32_e32 v80, 0x3f317217, v65
	v_cmp_lt_f32_e64 s[14:15], |v65|, s58
	s_nop 1
	v_cndmask_b32_e64 v65, v65, v80, s[14:15]
	v_cndmask_b32_e32 v80, 0, v242, vcc
	v_sub_f32_e32 v65, v65, v80
	v_max_f32_e32 v65, 0xc2700000, v65
	v_add_f32_e32 v65, v65, v73
	s_mov_b64 s[14:15], -1
	s_and_b64 vcc, exec, s[16:17]
	ds_write_b32 v36, v65 offset:36864
	s_waitcnt vmcnt(9)
	ds_write_b16 v19, v0 offset:18432
	ds_write_b16_d16_hi v19, v0 offset:18576
	ds_write_b16 v19, v1 offset:18720
	ds_write_b16_d16_hi v19, v1 offset:18864
	ds_write_b16 v19, v2 offset:19008
	ds_write_b16_d16_hi v19, v2 offset:19152
	ds_write_b16 v19, v3 offset:19296
	ds_write_b16_d16_hi v39, v3 offset:18432
	s_waitcnt vmcnt(8)
	ds_write_b16 v40, v6 offset:18432
	ds_write_b16_d16_hi v40, v6 offset:18576
	ds_write_b16 v40, v7 offset:18720
	ds_write_b16_d16_hi v40, v7 offset:18864
	ds_write_b16 v40, v8 offset:19008
	ds_write_b16_d16_hi v40, v8 offset:19152
	ds_write_b16 v40, v9 offset:19296
	ds_write_b16_d16_hi v41, v9 offset:18432
	s_cbranch_vccz .LBB0_425
	s_andn2_b64 vcc, exec, s[18:19]
	s_mov_b32 s44, -1
	s_cbranch_vccnz .LBB0_420
	s_and_b64 vcc, exec, s[20:21]
	s_cbranch_vccz .LBB0_418
	s_cmp_lt_u32 s34, 8
	s_mov_b32 s44, s38
	s_cbranch_scc1 .LBB0_417
	s_cmp_eq_u32 s34, 8
	s_cselect_b64 s[14:15], -1, 0
	s_and_b64 s[14:15], s[14:15], s[24:25]
	s_and_b64 s[14:15], s[14:15], exec
	s_cselect_b32 s44, s31, -1

; __device__ __forceinline__ unsigned cvt_pk_bf16(float lo, float hi) { unsigned r; asm("v_cvt_pk_bf16_f32 %0, %1, %2" : "=v"(r) : "v"(lo), "v"(hi)); return r; }
;     __device__ __forceinline__ void operator()(const f32x4 (&acc)[2][2][4][2], const Unit& u, int wr, int wc, int fr, int fq) const {
;         const int row0 = u.pm * 256 + wr * 64 + fr, colt = u.pn * 256 + wc * 32 + 8 * fq;
; #pragma unroll
;         for (int ai = 0; ai < 2; ++ai)
; #pragma unroll
;             for (int m = 0; m < 4; ++m) {
;                 const int row = row0 + ai * 128 + m * 16; const float rs = rsqrtf(sumsq[row] * (1.f / 1024.f) + EPS);
; #pragma unroll
;                 for (int bj = 0; bj < 2; ++bj) {
;                     const f32x4 v0 = acc[ai][bj][m][0] * rs, v1 = acc[ai][bj][m][1] * rs;
;                     u32x4 w; w.x = cvt_pk_bf16(v0[0], v0[1]); w.y = cvt_pk_bf16(v0[2], v0[3]); w.z = cvt_pk_bf16(v1[0], v1[1]); w.w = cvt_pk_bf16(v1[2], v1[3]);
;                     *(u32x4*)(UV + (size_t)row * (2 * DFF) + colt + bj * 128) = w;
;                 }
;             }
.LBB0_573:
	v_lshl_add_u32 v140, s78, 8, v144
	v_ashrrev_i32_e32 v141, 31, v140
	v_lshl_add_u64 v[142:143], v[140:141], 2, s[14:15]
	global_load_dword v141, v[142:143], off
	global_load_dword v248, v[142:143], off offset:64
	global_load_dword v249, v[142:143], off offset:128
	global_load_dword v250, v[142:143], off offset:192
	global_load_dword v251, v[142:143], off offset:512
	global_load_dword v252, v[142:143], off offset:576
	global_load_dword v253, v[142:143], off offset:640
	global_load_dword v254, v[142:143], off offset:704
	s_load_dwordx2 s[24:25], s[0:1], 0x170
	v_lshl_or_b32 v148, s79, 8, v146
	v_ashrrev_i32_e32 v149, 31, v148
	s_mov_b32 s79, s76
	s_mov_b32 s78, s77
	s_mov_b64 s[26:27], s[8:9]
	s_waitcnt vmcnt(0)
	v_fmamk_f32 v141, v141, 0x3a800000, v236
	v_cmp_gt_f32_e32 vcc, s37, v141
	v_mul_f32_e32 v150, 0x4b800000, v141
	s_nop 0
	v_cndmask_b32_e32 v141, v141, v150, vcc
	v_rsq_f32_e32 v141, v141
	s_nop 0
	v_mul_f32_e32 v150, 0x45800000, v141
	v_cndmask_b32_e32 v150, v141, v150, vcc
	v_pk_mul_f32 v[122:123], v[122:123], v[150:151] op_sel_hi:[1,0]
	v_pk_mul_f32 v[124:125], v[124:125], v[150:151] op_sel_hi:[1,0]
	v_pk_mul_f32 v[152:153], v[128:129], v[150:151] op_sel_hi:[1,0]
	v_pk_mul_f32 v[128:129], v[126:127], v[150:151] op_sel_hi:[1,0]
	v_cvt_pk_bf16_f32 v126, v122, v123
	s_waitcnt lgkmcnt(0)
	v_mov_b64_e32 v[122:123], s[24:25]
	v_cvt_pk_bf16_f32 v127, v124, v125
	v_cvt_pk_bf16_f32 v128, v128, v129
	v_cvt_pk_bf16_f32 v129, v152, v153
	v_mad_i64_i32 v[152:153], s[24:25], v140, s95, v[122:123]
	v_lshlrev_b64 v[124:125], 1, v[148:149]
	v_lshl_add_u64 v[148:149], v[152:153], 0, v[124:125]
	global_store_dwordx4 v[148:149], v[126:129], off
	v_pk_mul_f32 v[120:121], v[120:121], v[150:151] op_sel_hi:[1,0]
	v_pk_mul_f32 v[118:119], v[118:119], v[150:151] op_sel_hi:[1,0]
	v_pk_mul_f32 v[126:127], v[116:117], v[150:151] op_sel_hi:[1,0]
	v_pk_mul_f32 v[116:117], v[114:115], v[150:151] op_sel_hi:[1,0]
	v_cvt_pk_bf16_f32 v114, v118, v119
	v_cvt_pk_bf16_f32 v115, v120, v121
	s_nop 0
	v_cvt_pk_bf16_f32 v116, v116, v117
	v_cvt_pk_bf16_f32 v117, v126, v127
	global_store_dwordx4 v[148:149], v[114:117], off offset:256
	s_nop 1
	v_mov_b32_e32 v114, v248
	s_nop 0
	v_or_b32_e32 v115, 16, v140
	v_fmamk_f32 v114, v114, 0x3a800000, v236
	v_cmp_gt_f32_e32 vcc, s37, v114
	v_mul_f32_e32 v116, 0x4b800000, v114
	s_nop 0
	v_cndmask_b32_e32 v114, v114, v116, vcc
	v_rsq_f32_e32 v114, v114
	s_nop 0
	v_mul_f32_e32 v116, 0x45800000, v114
	v_cndmask_b32_e32 v114, v114, v116, vcc
	v_pk_mul_f32 v[110:111], v[110:111], v[114:115] op_sel_hi:[1,0]
	v_pk_mul_f32 v[116:117], v[108:109], v[114:115] op_sel_hi:[1,0]
	v_pk_mul_f32 v[108:109], v[106:107], v[114:115] op_sel_hi:[1,0]
	v_cvt_pk_bf16_f32 v106, v110, v111
	v_mad_i64_i32 v[110:111], s[24:25], v115, s95, v[122:123]
	v_pk_mul_f32 v[112:113], v[112:113], v[114:115] op_sel_hi:[1,0]
	v_lshl_add_u64 v[110:111], v[110:111], 0, v[124:125]
	v_cvt_pk_bf16_f32 v107, v112, v113
	v_cvt_pk_bf16_f32 v108, v108, v109
	v_cvt_pk_bf16_f32 v109, v116, v117
	global_store_dwordx4 v[110:111], v[106:109], off
	v_pk_mul_f32 v[104:105], v[104:105], v[114:115] op_sel_hi:[1,0]
	v_pk_mul_f32 v[102:103], v[102:103], v[114:115] op_sel_hi:[1,0]
	v_pk_mul_f32 v[106:107], v[100:101], v[114:115] op_sel_hi:[1,0]
	v_pk_mul_f32 v[100:101], v[98:99], v[114:115] op_sel_hi:[1,0]
	v_cvt_pk_bf16_f32 v98, v102, v103
	v_cvt_pk_bf16_f32 v99, v104, v105
	s_nop 0
	v_cvt_pk_bf16_f32 v100, v100, v101
	v_cvt_pk_bf16_f32 v101, v106, v107
	global_store_dwordx4 v[110:111], v[98:101], off offset:256
	s_nop 1
	v_mov_b32_e32 v98, v249
	s_nop 0
	v_or_b32_e32 v99, 32, v140
	v_fmamk_f32 v98, v98, 0x3a800000, v236
	v_cmp_gt_f32_e32 vcc, s37, v98
	v_mul_f32_e32 v100, 0x4b800000, v98
	s_nop 0
	v_cndmask_b32_e32 v98, v98, v100, vcc
	v_rsq_f32_e32 v98, v98
	s_nop 0
	v_mul_f32_e32 v100, 0x45800000, v98
	v_cndmask_b32_e32 v98, v98, v100, vcc
	v_pk_mul_f32 v[94:95], v[94:95], v[98:99] op_sel_hi:[1,0]
	v_pk_mul_f32 v[100:101], v[92:93], v[98:99] op_sel_hi:[1,0]
	v_pk_mul_f32 v[92:93], v[90:91], v[98:99] op_sel_hi:[1,0]
	v_cvt_pk_bf16_f32 v90, v94, v95
	v_mad_i64_i32 v[94:95], s[24:25], v99, s95, v[122:123]
	v_pk_mul_f32 v[96:97], v[96:97], v[98:99] op_sel_hi:[1,0]
	v_lshl_add_u64 v[94:95], v[94:95], 0, v[124:125]
	v_cvt_pk_bf16_f32 v91, v96, v97
	v_cvt_pk_bf16_f32 v92, v92, v93
	v_cvt_pk_bf16_f32 v93, v100, v101
	global_store_dwordx4 v[94:95], v[90:93], off
	v_pk_mul_f32 v[88:89], v[88:89], v[98:99] op_sel_hi:[1,0]
	v_pk_mul_f32 v[86:87], v[86:87], v[98:99] op_sel_hi:[1,0]
	v_pk_mul_f32 v[90:91], v[84:85], v[98:99] op_sel_hi:[1,0]
	v_pk_mul_f32 v[84:85], v[82:83], v[98:99] op_sel_hi:[1,0]
	v_cvt_pk_bf16_f32 v82, v86, v87
	v_cvt_pk_bf16_f32 v83, v88, v89
	s_nop 0
	v_cvt_pk_bf16_f32 v84, v84, v85
	v_cvt_pk_bf16_f32 v85, v90, v91
	global_store_dwordx4 v[94:95], v[82:85], off offset:256
	s_nop 1
	v_mov_b32_e32 v82, v250
	s_nop 0
	v_or_b32_e32 v83, 48, v140
	v_fmamk_f32 v82, v82, 0x3a800000, v236
	v_cmp_gt_f32_e32 vcc, s37, v82
	v_mul_f32_e32 v84, 0x4b800000, v82
	s_nop 0
	v_cndmask_b32_e32 v82, v82, v84, vcc
	v_rsq_f32_e32 v82, v82
	s_nop 0
	v_mul_f32_e32 v84, 0x45800000, v82
	v_cndmask_b32_e32 v82, v82, v84, vcc
	v_pk_mul_f32 v[78:79], v[78:79], v[82:83] op_sel_hi:[1,0]
	v_pk_mul_f32 v[84:85], v[76:77], v[82:83] op_sel_hi:[1,0]
	v_pk_mul_f32 v[76:77], v[74:75], v[82:83] op_sel_hi:[1,0]
	v_cvt_pk_bf16_f32 v74, v78, v79
	v_mad_i64_i32 v[78:79], s[24:25], v83, s95, v[122:123]
	v_pk_mul_f32 v[80:81], v[80:81], v[82:83] op_sel_hi:[1,0]
	v_lshl_add_u64 v[78:79], v[78:79], 0, v[124:125]
	v_cvt_pk_bf16_f32 v75, v80, v81
	v_cvt_pk_bf16_f32 v76, v76, v77
	v_cvt_pk_bf16_f32 v77, v84, v85
; __device__ __forceinline__ unsigned cvt_pk_bf16(float lo, float hi) { unsigned r; asm("v_cvt_pk_bf16_f32 %0, %1, %2" : "=v"(r) : "v"(lo), "v"(hi)); return r; }
;     __device__ __forceinline__ void operator()(const f32x4 (&acc)[2][2][4][2], const Unit& u, int wr, int wc, int fr, int fq) const {
;         const int row0 = u.pm * 256 + wr * 64 + fr, colt = u.pn * 256 + wc * 32 + 8 * fq;
; #pragma unroll
;         for (int ai = 0; ai < 2; ++ai)
; #pragma unroll
;             for (int m = 0; m < 4; ++m) {
;                 const int row = row0 + ai * 128 + m * 16; const float rs = rsqrtf(sumsq[row] * (1.f / 1024.f) + EPS);
; #pragma unroll
;                 for (int bj = 0; bj < 2; ++bj) {
;                     const f32x4 v0 = acc[ai][bj][m][0] * rs, v1 = acc[ai][bj][m][1] * rs;
;                     u32x4 w; w.x = cvt_pk_bf16(v0[0], v0[1]); w.y = cvt_pk_bf16(v0[2], v0[3]); w.z = cvt_pk_bf16(v1[0], v1[1]); w.w = cvt_pk_bf16(v1[2], v1[3]);
;                     *(u32x4*)(UV + (size_t)row * (2 * DFF) + colt + bj * 128) = w;
;                 }
;             }
	global_store_dwordx4 v[78:79], v[74:77], off
	v_pk_mul_f32 v[72:73], v[72:73], v[82:83] op_sel_hi:[1,0]
	v_pk_mul_f32 v[70:71], v[70:71], v[82:83] op_sel_hi:[1,0]
	v_pk_mul_f32 v[74:75], v[68:69], v[82:83] op_sel_hi:[1,0]
	v_pk_mul_f32 v[68:69], v[66:67], v[82:83] op_sel_hi:[1,0]
	v_cvt_pk_bf16_f32 v66, v70, v71
	v_cvt_pk_bf16_f32 v67, v72, v73
	s_nop 0
	v_cvt_pk_bf16_f32 v68, v68, v69
	v_cvt_pk_bf16_f32 v69, v74, v75
	global_store_dwordx4 v[78:79], v[66:69], off offset:256
	s_nop 1
	v_mov_b32_e32 v66, v251
	s_nop 0
	v_add_u32_e32 v67, 0x80, v140
	v_fmamk_f32 v66, v66, 0x3a800000, v236
	v_cmp_gt_f32_e32 vcc, s37, v66
	v_mul_f32_e32 v68, 0x4b800000, v66
	s_nop 0
	v_cndmask_b32_e32 v66, v66, v68, vcc
	v_rsq_f32_e32 v66, v66
	s_nop 0
	v_mul_f32_e32 v68, 0x45800000, v66
	v_cndmask_b32_e32 v66, v66, v68, vcc
	v_pk_mul_f32 v[62:63], v[62:63], v[66:67] op_sel_hi:[1,0]
	v_pk_mul_f32 v[68:69], v[60:61], v[66:67] op_sel_hi:[1,0]
	v_pk_mul_f32 v[60:61], v[58:59], v[66:67] op_sel_hi:[1,0]
	v_cvt_pk_bf16_f32 v58, v62, v63
	v_mad_i64_i32 v[62:63], s[24:25], v67, s95, v[122:123]
	v_pk_mul_f32 v[64:65], v[64:65], v[66:67] op_sel_hi:[1,0]
	v_lshl_add_u64 v[62:63], v[62:63], 0, v[124:125]
	v_cvt_pk_bf16_f32 v59, v64, v65
	v_cvt_pk_bf16_f32 v60, v60, v61
	v_cvt_pk_bf16_f32 v61, v68, v69
	global_store_dwordx4 v[62:63], v[58:61], off
	v_pk_mul_f32 v[56:57], v[56:57], v[66:67] op_sel_hi:[1,0]
	v_pk_mul_f32 v[54:55], v[54:55], v[66:67] op_sel_hi:[1,0]
	v_pk_mul_f32 v[58:59], v[52:53], v[66:67] op_sel_hi:[1,0]
	v_pk_mul_f32 v[52:53], v[50:51], v[66:67] op_sel_hi:[1,0]
	v_cvt_pk_bf16_f32 v50, v54, v55
	v_cvt_pk_bf16_f32 v51, v56, v57
	s_nop 0
	v_cvt_pk_bf16_f32 v52, v52, v53
	v_cvt_pk_bf16_f32 v53, v58, v59
	global_store_dwordx4 v[62:63], v[50:53], off offset:256
	s_nop 1
	v_mov_b32_e32 v50, v252
	s_nop 0
	v_add_u32_e32 v51, 0x90, v140
	v_fmamk_f32 v50, v50, 0x3a800000, v236
	v_cmp_gt_f32_e32 vcc, s37, v50
	v_mul_f32_e32 v52, 0x4b800000, v50
	s_nop 0
	v_cndmask_b32_e32 v50, v50, v52, vcc
	v_rsq_f32_e32 v50, v50
	s_nop 0
	v_mul_f32_e32 v52, 0x45800000, v50
	v_cndmask_b32_e32 v50, v50, v52, vcc
	v_pk_mul_f32 v[46:47], v[46:47], v[50:51] op_sel_hi:[1,0]
	v_pk_mul_f32 v[52:53], v[44:45], v[50:51] op_sel_hi:[1,0]
	v_pk_mul_f32 v[44:45], v[42:43], v[50:51] op_sel_hi:[1,0]
	v_cvt_pk_bf16_f32 v42, v46, v47
	v_mad_i64_i32 v[46:47], s[24:25], v51, s95, v[122:123]
	v_pk_mul_f32 v[48:49], v[48:49], v[50:51] op_sel_hi:[1,0]
	v_lshl_add_u64 v[46:47], v[46:47], 0, v[124:125]
	v_cvt_pk_bf16_f32 v43, v48, v49
	v_cvt_pk_bf16_f32 v44, v44, v45
	v_cvt_pk_bf16_f32 v45, v52, v53
	global_store_dwordx4 v[46:47], v[42:45], off
	v_pk_mul_f32 v[40:41], v[40:41], v[50:51] op_sel_hi:[1,0]
	v_pk_mul_f32 v[38:39], v[38:39], v[50:51] op_sel_hi:[1,0]
	v_pk_mul_f32 v[42:43], v[36:37], v[50:51] op_sel_hi:[1,0]
	v_pk_mul_f32 v[36:37], v[34:35], v[50:51] op_sel_hi:[1,0]
	v_cvt_pk_bf16_f32 v34, v38, v39
	v_cvt_pk_bf16_f32 v35, v40, v41
	s_nop 0
	v_cvt_pk_bf16_f32 v36, v36, v37
	v_cvt_pk_bf16_f32 v37, v42, v43
	global_store_dwordx4 v[46:47], v[34:37], off offset:256
	s_nop 1
	v_mov_b32_e32 v34, v253
	s_nop 0
	v_add_u32_e32 v35, 0xa0, v140
	v_fmamk_f32 v34, v34, 0x3a800000, v236
	v_cmp_gt_f32_e32 vcc, s37, v34
	v_mul_f32_e32 v36, 0x4b800000, v34
	s_nop 0
	v_cndmask_b32_e32 v34, v34, v36, vcc
	v_rsq_f32_e32 v34, v34
	s_nop 0
	v_mul_f32_e32 v36, 0x45800000, v34
	v_cndmask_b32_e32 v34, v34, v36, vcc
	v_pk_mul_f32 v[30:31], v[30:31], v[34:35] op_sel_hi:[1,0]
	v_pk_mul_f32 v[36:37], v[28:29], v[34:35] op_sel_hi:[1,0]
	v_pk_mul_f32 v[28:29], v[26:27], v[34:35] op_sel_hi:[1,0]
	v_cvt_pk_bf16_f32 v26, v30, v31
	v_mad_i64_i32 v[30:31], s[24:25], v35, s95, v[122:123]
	v_pk_mul_f32 v[32:33], v[32:33], v[34:35] op_sel_hi:[1,0]
	v_lshl_add_u64 v[30:31], v[30:31], 0, v[124:125]
	v_cvt_pk_bf16_f32 v27, v32, v33
	v_cvt_pk_bf16_f32 v28, v28, v29
	v_cvt_pk_bf16_f32 v29, v36, v37
	global_store_dwordx4 v[30:31], v[26:29], off
	v_pk_mul_f32 v[24:25], v[24:25], v[34:35] op_sel_hi:[1,0]
	v_pk_mul_f32 v[22:23], v[22:23], v[34:35] op_sel_hi:[1,0]
	v_pk_mul_f32 v[26:27], v[20:21], v[34:35] op_sel_hi:[1,0]
	v_pk_mul_f32 v[20:21], v[18:19], v[34:35] op_sel_hi:[1,0]
	v_cvt_pk_bf16_f32 v18, v22, v23
	v_cvt_pk_bf16_f32 v19, v24, v25
	s_nop 0
	v_cvt_pk_bf16_f32 v20, v20, v21
	v_cvt_pk_bf16_f32 v21, v26, v27
	global_store_dwordx4 v[30:31], v[18:21], off offset:256
	s_nop 1
	v_mov_b32_e32 v18, v254
	s_nop 0
	v_add_u32_e32 v19, 0xb0, v140
	v_fmamk_f32 v18, v18, 0x3a800000, v236
	v_cmp_gt_f32_e32 vcc, s37, v18
	v_mul_f32_e32 v20, 0x4b800000, v18
	s_nop 0
	v_cndmask_b32_e32 v18, v18, v20, vcc
	v_rsq_f32_e32 v18, v18
	s_nop 0
	v_mul_f32_e32 v20, 0x45800000, v18
	v_cndmask_b32_e32 v18, v18, v20, vcc
	v_pk_mul_f32 v[14:15], v[14:15], v[18:19] op_sel_hi:[1,0]
	v_pk_mul_f32 v[20:21], v[12:13], v[18:19] op_sel_hi:[1,0]
	v_pk_mul_f32 v[12:13], v[10:11], v[18:19] op_sel_hi:[1,0]
	v_cvt_pk_bf16_f32 v10, v14, v15
	v_mad_i64_i32 v[14:15], s[24:25], v19, s95, v[122:123]
	v_pk_mul_f32 v[16:17], v[16:17], v[18:19] op_sel_hi:[1,0]
	v_lshl_add_u64 v[14:15], v[14:15], 0, v[124:125]
	v_cvt_pk_bf16_f32 v11, v16, v17
	v_cvt_pk_bf16_f32 v12, v12, v13
	v_cvt_pk_bf16_f32 v13, v20, v21
	global_store_dwordx4 v[14:15], v[10:13], off
	s_and_b64 vcc, exec, s[4:5]
	s_mov_b64 s[24:25], s[6:7]
	v_pk_mul_f32 v[10:11], v[2:3], v[18:19] op_sel_hi:[1,0]
	v_pk_mul_f32 v[2:3], v[0:1], v[18:19] op_sel_hi:[1,0]
	v_pk_mul_f32 v[8:9], v[8:9], v[18:19] op_sel_hi:[1,0]
	v_pk_mul_f32 v[6:7], v[6:7], v[18:19] op_sel_hi:[1,0]
	v_cvt_pk_bf16_f32 v1, v8, v9
	v_cvt_pk_bf16_f32 v2, v2, v3
	v_cvt_pk_bf16_f32 v3, v10, v11
	s_nop 0
	v_cvt_pk_bf16_f32 v0, v6, v7
	global_store_dwordx4 v[14:15], v[0:3], off offset:256
	s_cbranch_vccnz .LBB0_583

; __device__ __forceinline__ unsigned cvt_pk_bf16(float lo, float hi) { unsigned r; asm("v_cvt_pk_bf16_f32 %0, %1, %2" : "=v"(r) : "v"(lo), "v"(hi)); return r; }
;     __device__ __forceinline__ void operator()(const f32x4 (&acc)[2][2][4][2], const Unit& u, int wr, int wc, int fr, int fq) const {
;         const int row0 = u.pm * 256 + wr * 64 + fr, colt = u.pn * 256 + wc * 32 + 8 * fq;
; #pragma unroll
;         for (int ai = 0; ai < 2; ++ai)
; #pragma unroll
;             for (int m = 0; m < 4; ++m) {
;                 const int row = row0 + ai * 128 + m * 16; const float rs = rsqrtf(sumsq[row] * (1.f / 1024.f) + EPS);
; #pragma unroll
;                 for (int bj = 0; bj < 2; ++bj) {
;                     const f32x4 v0 = acc[ai][bj][m][0] * rs, v1 = acc[ai][bj][m][1] * rs; const int col = colt + bj * 128;
;                     u32x4 w; w.x = cvt_pk_bf16(v0[0], v0[1]); w.y = cvt_pk_bf16(v0[2], v0[3]); w.z = cvt_pk_bf16(v1[0], v1[1]); w.w = cvt_pk_bf16(v1[2], v1[3]);
;                     *(u32x4*)(P + (size_t)row * NIN + col) = w;
;                     if (u.pn >= 8 && u.pn < 16) {
;                         float* dst; int c2;
;                         if (u.pn < 12) { c2 = col - C_KB; dst = row < SEQ ? kp + (size_t)row * 1024 : ks + (size_t)(row - SEQ) * 1024; }
;                         else { c2 = col - C_VB; dst = row < SEQ ? vp + (size_t)row * 1024 : vs + (size_t)(row - SEQ) * 1024; }
;                         __builtin_nontemporal_store(v0, (f32x4*)(dst + c2)); __builtin_nontemporal_store(v1, (f32x4*)(dst + c2 + 4));
;                     }
.LBB0_826:
	v_lshl_add_u32 v144, s87, 8, v160
	v_ashrrev_i32_e32 v145, 31, v144
	v_lshl_add_u64 v[146:147], v[144:145], 2, s[18:19]
	global_load_dword v4, v[146:147], off
	global_load_dword v248, v[146:147], off offset:64
	global_load_dword v249, v[146:147], off offset:128
	global_load_dword v250, v[146:147], off offset:192
	global_load_dword v251, v[146:147], off offset:512
	global_load_dword v252, v[146:147], off offset:576
	global_load_dword v253, v[146:147], off offset:640
	global_load_dword v254, v[146:147], off offset:704
	s_and_b32 s8, s86, -8
	s_cmp_eq_u32 s8, 8
	v_lshl_or_b32 v142, s86, 8, v162
	s_cselect_b64 s[6:7], -1, 0
	s_cmp_gt_u32 s86, 11
	s_waitcnt lgkmcnt(0)
	v_mov_b64_e32 v[154:155], s[24:25]
	s_cselect_b64 s[46:47], -1, 0
	s_cmp_lg_u32 s8, 8
	v_mad_i64_i32 v[154:155], s[8:9], v144, s43, v[154:155]
	v_cmp_lt_i32_e64 s[10:11], s65, v144
	v_lshlrev_b64 v[148:149], 12, v[144:145]
	s_waitcnt vmcnt(0)
	v_fmamk_f32 v4, v4, 0x3a800000, v236
	v_cmp_gt_f32_e32 vcc, s37, v4
	v_mul_f32_e32 v143, 0x4b800000, v4
	s_nop 0
	v_cndmask_b32_e32 v4, v4, v143, vcc
	v_rsq_f32_e32 v4, v4
	s_nop 0
	v_mul_f32_e32 v143, 0x45800000, v4
	v_cndmask_b32_e32 v152, v4, v143, vcc
	v_add_u32_e32 v4, 0xffffc000, v144
	v_ashrrev_i32_e32 v143, 31, v142
	v_lshlrev_b64 v[150:151], 12, v[4:5]
	v_pk_mul_f32 v[124:125], v[124:125], v[152:153] op_sel_hi:[1,0]
	v_pk_mul_f32 v[122:123], v[122:123], v[152:153] op_sel_hi:[1,0]
	v_pk_mul_f32 v[128:129], v[128:129], v[152:153] op_sel_hi:[1,0]
	v_pk_mul_f32 v[126:127], v[126:127], v[152:153] op_sel_hi:[1,0]
	v_lshl_add_u64 v[154:155], v[142:143], 1, v[154:155]
	v_cvt_pk_bf16_f32 v156, v122, v123
	v_cvt_pk_bf16_f32 v157, v124, v125
	v_cvt_pk_bf16_f32 v158, v126, v127
	v_cvt_pk_bf16_f32 v159, v128, v129
	global_store_dwordx4 v[154:155], v[156:159], off
	s_cbranch_scc1 .LBB0_840
	s_mov_b64 s[8:9], -1
	s_and_b64 vcc, exec, s[46:47]
	s_cbranch_vccz .LBB0_833
	s_and_saveexec_b64 s[8:9], s[10:11]
	s_xor_b64 s[8:9], exec, s[8:9]
	v_lshl_add_u64 v[156:157], s[30:31], 0, v[150:151]
	s_andn2_saveexec_b64 s[8:9], s[8:9]
	v_lshl_add_u64 v[156:157], s[28:29], 0, v[148:149]
	s_or_b64 exec, exec, s[8:9]
	v_add_u32_e32 v158, 0xfffff400, v142
	s_mov_b64 s[8:9], 0

; __device__ __forceinline__ unsigned cvt_pk_bf16(float lo, float hi) { unsigned r; asm("v_cvt_pk_bf16_f32 %0, %1, %2" : "=v"(r) : "v"(lo), "v"(hi)); return r; }
;     __device__ __forceinline__ void operator()(const f32x4 (&acc)[2][2][4][2], const Unit& u, int wr, int wc, int fr, int fq) const {
;     ...
;             for (int m = 0; m < 4; ++m) {
;                 const int row = row0 + ai * 128 + m * 16; const float rs = rsqrtf(sumsq[row] * (1.f / 1024.f) + EPS);
; #pragma unroll
;                 for (int bj = 0; bj < 2; ++bj) {
;                     const f32x4 v0 = acc[ai][bj][m][0] * rs, v1 = acc[ai][bj][m][1] * rs; const int col = colt + bj * 128;
;                     u32x4 w; w.x = cvt_pk_bf16(v0[0], v0[1]); w.y = cvt_pk_bf16(v0[2], v0[3]); w.z = cvt_pk_bf16(v1[0], v1[1]); w.w = cvt_pk_bf16(v1[2], v1[3]);
;                     *(u32x4*)(P + (size_t)row * NIN + col) = w;
;                     if (u.pn >= 8 && u.pn < 16) {
;                         float* dst; int c2;
;                         if (u.pn < 12) { c2 = col - C_KB; dst = row < SEQ ? kp + (size_t)row * 1024 : ks + (size_t)(row - SEQ) * 1024; }
;                         else { c2 = col - C_VB; dst = row < SEQ ? vp + (size_t)row * 1024 : vs + (size_t)(row - SEQ) * 1024; }
;                         __builtin_nontemporal_store(v0, (f32x4*)(dst + c2)); __builtin_nontemporal_store(v1, (f32x4*)(dst + c2 + 4));
;                     }
.LBB0_854:
	s_nop 1
	v_mov_b32_e32 v4, v248
	v_or_b32_e32 v120, 16, v144
	v_ashrrev_i32_e32 v121, 31, v120
	v_mov_b64_e32 v[126:127], s[24:25]
	v_cmp_lt_i32_e64 s[10:11], s65, v120
	v_fmamk_f32 v4, v4, 0x3a800000, v236
	v_cmp_gt_f32_e32 vcc, s37, v4
	v_mul_f32_e32 v114, 0x4b800000, v4
	s_nop 0
	v_cndmask_b32_e32 v4, v4, v114, vcc
	v_rsq_f32_e32 v4, v4
	s_nop 0
	v_mul_f32_e32 v114, 0x45800000, v4
	v_cndmask_b32_e32 v118, v4, v114, vcc
	v_add_u32_e32 v4, 0xffffc010, v144
	v_lshlrev_b64 v[114:115], 12, v[120:121]
	v_mad_i64_i32 v[120:121], s[46:47], v120, s43, v[126:127]
	v_lshlrev_b64 v[116:117], 12, v[4:5]
	v_pk_mul_f32 v[112:113], v[112:113], v[118:119] op_sel_hi:[1,0]
	v_pk_mul_f32 v[110:111], v[110:111], v[118:119] op_sel_hi:[1,0]
	v_pk_mul_f32 v[108:109], v[108:109], v[118:119] op_sel_hi:[1,0]
	v_pk_mul_f32 v[106:107], v[106:107], v[118:119] op_sel_hi:[1,0]
	v_lshl_add_u64 v[120:121], v[142:143], 1, v[120:121]
	s_and_b64 vcc, exec, s[8:9]
	v_cvt_pk_bf16_f32 v122, v110, v111
	v_cvt_pk_bf16_f32 v123, v112, v113
	v_cvt_pk_bf16_f32 v124, v106, v107
	v_cvt_pk_bf16_f32 v125, v108, v109
	global_store_dwordx4 v[120:121], v[122:125], off
	s_cbranch_vccnz .LBB0_868
	s_and_b64 vcc, exec, s[6:7]
	s_mov_b64 s[46:47], -1
	s_cbranch_vccnz .LBB0_861
	s_and_saveexec_b64 s[46:47], s[10:11]
	s_xor_b64 s[46:47], exec, s[46:47]
	v_lshl_add_u64 v[122:123], s[30:31], 0, v[116:117]
	s_andn2_saveexec_b64 s[46:47], s[46:47]
	v_lshl_add_u64 v[122:123], s[28:29], 0, v[114:115]
	s_or_b64 exec, exec, s[46:47]
	v_add_u32_e32 v124, 0xfffff400, v142
	s_mov_b64 s[46:47], 0

; __device__ __forceinline__ unsigned cvt_pk_bf16(float lo, float hi) { unsigned r; asm("v_cvt_pk_bf16_f32 %0, %1, %2" : "=v"(r) : "v"(lo), "v"(hi)); return r; }
;     __device__ __forceinline__ void operator()(const f32x4 (&acc)[2][2][4][2], const Unit& u, int wr, int wc, int fr, int fq) const {
;     ...
;             for (int m = 0; m < 4; ++m) {
;                 const int row = row0 + ai * 128 + m * 16; const float rs = rsqrtf(sumsq[row] * (1.f / 1024.f) + EPS);
; #pragma unroll
;                 for (int bj = 0; bj < 2; ++bj) {
;                     const f32x4 v0 = acc[ai][bj][m][0] * rs, v1 = acc[ai][bj][m][1] * rs; const int col = colt + bj * 128;
;                     u32x4 w; w.x = cvt_pk_bf16(v0[0], v0[1]); w.y = cvt_pk_bf16(v0[2], v0[3]); w.z = cvt_pk_bf16(v1[0], v1[1]); w.w = cvt_pk_bf16(v1[2], v1[3]);
;                     *(u32x4*)(P + (size_t)row * NIN + col) = w;
;                     if (u.pn >= 8 && u.pn < 16) {
;                         float* dst; int c2;
;                         if (u.pn < 12) { c2 = col - C_KB; dst = row < SEQ ? kp + (size_t)row * 1024 : ks + (size_t)(row - SEQ) * 1024; }
;                         else { c2 = col - C_VB; dst = row < SEQ ? vp + (size_t)row * 1024 : vs + (size_t)(row - SEQ) * 1024; }
;                         __builtin_nontemporal_store(v0, (f32x4*)(dst + c2)); __builtin_nontemporal_store(v1, (f32x4*)(dst + c2 + 4));
;                     }
.LBB0_882:
	s_nop 1
	v_mov_b32_e32 v4, v249
	v_or_b32_e32 v104, 32, v144
	v_ashrrev_i32_e32 v105, 31, v104
	v_mov_b64_e32 v[110:111], s[24:25]
	v_cmp_lt_i32_e64 s[10:11], s65, v104
	v_fmamk_f32 v4, v4, 0x3a800000, v236
	v_cmp_gt_f32_e32 vcc, s37, v4
	v_mul_f32_e32 v98, 0x4b800000, v4
	s_nop 0
	v_cndmask_b32_e32 v4, v4, v98, vcc
	v_rsq_f32_e32 v4, v4
	s_nop 0
	v_mul_f32_e32 v98, 0x45800000, v4
	v_cndmask_b32_e32 v102, v4, v98, vcc
	v_add_u32_e32 v4, 0xffffc020, v144
	v_lshlrev_b64 v[98:99], 12, v[104:105]
	v_mad_i64_i32 v[104:105], s[46:47], v104, s43, v[110:111]
	v_lshlrev_b64 v[100:101], 12, v[4:5]
	v_pk_mul_f32 v[96:97], v[96:97], v[102:103] op_sel_hi:[1,0]
	v_pk_mul_f32 v[94:95], v[94:95], v[102:103] op_sel_hi:[1,0]
	v_pk_mul_f32 v[92:93], v[92:93], v[102:103] op_sel_hi:[1,0]
	v_pk_mul_f32 v[90:91], v[90:91], v[102:103] op_sel_hi:[1,0]
	v_lshl_add_u64 v[104:105], v[142:143], 1, v[104:105]
	s_and_b64 vcc, exec, s[8:9]
	v_cvt_pk_bf16_f32 v106, v94, v95
	v_cvt_pk_bf16_f32 v107, v96, v97
	v_cvt_pk_bf16_f32 v108, v90, v91
	v_cvt_pk_bf16_f32 v109, v92, v93
	global_store_dwordx4 v[104:105], v[106:109], off
	s_cbranch_vccnz .LBB0_896
	s_and_b64 vcc, exec, s[6:7]
	s_mov_b64 s[46:47], -1
	s_cbranch_vccnz .LBB0_889
	s_and_saveexec_b64 s[46:47], s[10:11]
	s_xor_b64 s[46:47], exec, s[46:47]
	v_lshl_add_u64 v[106:107], s[30:31], 0, v[100:101]
	s_andn2_saveexec_b64 s[46:47], s[46:47]
	v_lshl_add_u64 v[106:107], s[28:29], 0, v[98:99]
	s_or_b64 exec, exec, s[46:47]
	v_add_u32_e32 v108, 0xfffff400, v142
	s_mov_b64 s[46:47], 0

; __device__ __forceinline__ unsigned cvt_pk_bf16(float lo, float hi) { unsigned r; asm("v_cvt_pk_bf16_f32 %0, %1, %2" : "=v"(r) : "v"(lo), "v"(hi)); return r; }
;     __device__ __forceinline__ void operator()(const f32x4 (&acc)[2][2][4][2], const Unit& u, int wr, int wc, int fr, int fq) const {
;     ...
;             for (int m = 0; m < 4; ++m) {
;                 const int row = row0 + ai * 128 + m * 16; const float rs = rsqrtf(sumsq[row] * (1.f / 1024.f) + EPS);
; #pragma unroll
;                 for (int bj = 0; bj < 2; ++bj) {
;                     const f32x4 v0 = acc[ai][bj][m][0] * rs, v1 = acc[ai][bj][m][1] * rs; const int col = colt + bj * 128;
;                     u32x4 w; w.x = cvt_pk_bf16(v0[0], v0[1]); w.y = cvt_pk_bf16(v0[2], v0[3]); w.z = cvt_pk_bf16(v1[0], v1[1]); w.w = cvt_pk_bf16(v1[2], v1[3]);
;                     *(u32x4*)(P + (size_t)row * NIN + col) = w;
;                     if (u.pn >= 8 && u.pn < 16) {
;                         float* dst; int c2;
;                         if (u.pn < 12) { c2 = col - C_KB; dst = row < SEQ ? kp + (size_t)row * 1024 : ks + (size_t)(row - SEQ) * 1024; }
;                         else { c2 = col - C_VB; dst = row < SEQ ? vp + (size_t)row * 1024 : vs + (size_t)(row - SEQ) * 1024; }
;                         __builtin_nontemporal_store(v0, (f32x4*)(dst + c2)); __builtin_nontemporal_store(v1, (f32x4*)(dst + c2 + 4));
;                     }
.LBB0_910:
	s_nop 1
	v_mov_b32_e32 v4, v250
	v_or_b32_e32 v88, 48, v144
	v_ashrrev_i32_e32 v89, 31, v88
	v_mov_b64_e32 v[94:95], s[24:25]
	v_cmp_lt_i32_e64 s[10:11], s65, v88
	v_fmamk_f32 v4, v4, 0x3a800000, v236
	v_cmp_gt_f32_e32 vcc, s37, v4
	v_mul_f32_e32 v82, 0x4b800000, v4
	s_nop 0
	v_cndmask_b32_e32 v4, v4, v82, vcc
	v_rsq_f32_e32 v4, v4
	s_nop 0
	v_mul_f32_e32 v82, 0x45800000, v4
	v_cndmask_b32_e32 v86, v4, v82, vcc
	v_add_u32_e32 v4, 0xffffc030, v144
	v_lshlrev_b64 v[82:83], 12, v[88:89]
	v_mad_i64_i32 v[88:89], s[46:47], v88, s43, v[94:95]
	v_lshlrev_b64 v[84:85], 12, v[4:5]
	v_pk_mul_f32 v[80:81], v[80:81], v[86:87] op_sel_hi:[1,0]
	v_pk_mul_f32 v[78:79], v[78:79], v[86:87] op_sel_hi:[1,0]
	v_pk_mul_f32 v[76:77], v[76:77], v[86:87] op_sel_hi:[1,0]
	v_pk_mul_f32 v[74:75], v[74:75], v[86:87] op_sel_hi:[1,0]
	v_lshl_add_u64 v[88:89], v[142:143], 1, v[88:89]
	s_and_b64 vcc, exec, s[8:9]
	v_cvt_pk_bf16_f32 v90, v78, v79
	v_cvt_pk_bf16_f32 v91, v80, v81
	v_cvt_pk_bf16_f32 v92, v74, v75
	v_cvt_pk_bf16_f32 v93, v76, v77
	global_store_dwordx4 v[88:89], v[90:93], off
	s_cbranch_vccnz .LBB0_924
	s_and_b64 vcc, exec, s[6:7]
	s_mov_b64 s[46:47], -1
	s_cbranch_vccnz .LBB0_917
	s_and_saveexec_b64 s[46:47], s[10:11]
	s_xor_b64 s[46:47], exec, s[46:47]
	v_lshl_add_u64 v[90:91], s[30:31], 0, v[84:85]
	s_andn2_saveexec_b64 s[46:47], s[46:47]
	v_lshl_add_u64 v[90:91], s[28:29], 0, v[82:83]
	s_or_b64 exec, exec, s[46:47]
	v_add_u32_e32 v92, 0xfffff400, v142
	s_mov_b64 s[46:47], 0

; __device__ __forceinline__ unsigned cvt_pk_bf16(float lo, float hi) { unsigned r; asm("v_cvt_pk_bf16_f32 %0, %1, %2" : "=v"(r) : "v"(lo), "v"(hi)); return r; }
;     __device__ __forceinline__ void operator()(const f32x4 (&acc)[2][2][4][2], const Unit& u, int wr, int wc, int fr, int fq) const {
;     ...
;             for (int m = 0; m < 4; ++m) {
;                 const int row = row0 + ai * 128 + m * 16; const float rs = rsqrtf(sumsq[row] * (1.f / 1024.f) + EPS);
; #pragma unroll
;                 for (int bj = 0; bj < 2; ++bj) {
;                     const f32x4 v0 = acc[ai][bj][m][0] * rs, v1 = acc[ai][bj][m][1] * rs; const int col = colt + bj * 128;
;                     u32x4 w; w.x = cvt_pk_bf16(v0[0], v0[1]); w.y = cvt_pk_bf16(v0[2], v0[3]); w.z = cvt_pk_bf16(v1[0], v1[1]); w.w = cvt_pk_bf16(v1[2], v1[3]);
;                     *(u32x4*)(P + (size_t)row * NIN + col) = w;
;                     if (u.pn >= 8 && u.pn < 16) {
;                         float* dst; int c2;
;                         if (u.pn < 12) { c2 = col - C_KB; dst = row < SEQ ? kp + (size_t)row * 1024 : ks + (size_t)(row - SEQ) * 1024; }
;                         else { c2 = col - C_VB; dst = row < SEQ ? vp + (size_t)row * 1024 : vs + (size_t)(row - SEQ) * 1024; }
;                         __builtin_nontemporal_store(v0, (f32x4*)(dst + c2)); __builtin_nontemporal_store(v1, (f32x4*)(dst + c2 + 4));
;                     }
.LBB0_938:
	s_nop 1
	v_mov_b32_e32 v4, v251
	v_add_u32_e32 v72, 0x80, v144
	v_ashrrev_i32_e32 v73, 31, v72
	v_mov_b64_e32 v[78:79], s[24:25]
	s_movk_i32 s10, 0x3f7f
	v_cmp_lt_i32_e64 s[10:11], s10, v144
	v_fmamk_f32 v4, v4, 0x3a800000, v236
	v_cmp_gt_f32_e32 vcc, s37, v4
	v_mul_f32_e32 v66, 0x4b800000, v4
	s_nop 0
	v_cndmask_b32_e32 v4, v4, v66, vcc
	v_rsq_f32_e32 v4, v4
	s_nop 0
	v_mul_f32_e32 v66, 0x45800000, v4
	v_cndmask_b32_e32 v70, v4, v66, vcc
	v_add_u32_e32 v4, 0xffffc080, v144
	v_lshlrev_b64 v[66:67], 12, v[72:73]
	v_mad_i64_i32 v[72:73], s[46:47], v72, s43, v[78:79]
	v_lshlrev_b64 v[68:69], 12, v[4:5]
	v_pk_mul_f32 v[64:65], v[64:65], v[70:71] op_sel_hi:[1,0]
	v_pk_mul_f32 v[62:63], v[62:63], v[70:71] op_sel_hi:[1,0]
	v_pk_mul_f32 v[60:61], v[60:61], v[70:71] op_sel_hi:[1,0]
	v_pk_mul_f32 v[58:59], v[58:59], v[70:71] op_sel_hi:[1,0]
	v_lshl_add_u64 v[72:73], v[142:143], 1, v[72:73]
	s_and_b64 vcc, exec, s[8:9]
	v_cvt_pk_bf16_f32 v74, v62, v63
	v_cvt_pk_bf16_f32 v75, v64, v65
	v_cvt_pk_bf16_f32 v76, v58, v59
	v_cvt_pk_bf16_f32 v77, v60, v61
	global_store_dwordx4 v[72:73], v[74:77], off
	s_cbranch_vccnz .LBB0_952
	s_and_b64 vcc, exec, s[6:7]
	s_mov_b64 s[46:47], -1
	s_cbranch_vccnz .LBB0_945
	s_and_saveexec_b64 s[46:47], s[10:11]
	s_xor_b64 s[46:47], exec, s[46:47]
	v_lshl_add_u64 v[74:75], s[30:31], 0, v[68:69]
	s_andn2_saveexec_b64 s[46:47], s[46:47]
	v_lshl_add_u64 v[74:75], s[28:29], 0, v[66:67]
	s_or_b64 exec, exec, s[46:47]
	v_add_u32_e32 v76, 0xfffff400, v142
	s_mov_b64 s[46:47], 0

; __device__ __forceinline__ unsigned cvt_pk_bf16(float lo, float hi) { unsigned r; asm("v_cvt_pk_bf16_f32 %0, %1, %2" : "=v"(r) : "v"(lo), "v"(hi)); return r; }
;     __device__ __forceinline__ void operator()(const f32x4 (&acc)[2][2][4][2], const Unit& u, int wr, int wc, int fr, int fq) const {
;     ...
;             for (int m = 0; m < 4; ++m) {
;                 const int row = row0 + ai * 128 + m * 16; const float rs = rsqrtf(sumsq[row] * (1.f / 1024.f) + EPS);
; #pragma unroll
;                 for (int bj = 0; bj < 2; ++bj) {
;                     const f32x4 v0 = acc[ai][bj][m][0] * rs, v1 = acc[ai][bj][m][1] * rs; const int col = colt + bj * 128;
;                     u32x4 w; w.x = cvt_pk_bf16(v0[0], v0[1]); w.y = cvt_pk_bf16(v0[2], v0[3]); w.z = cvt_pk_bf16(v1[0], v1[1]); w.w = cvt_pk_bf16(v1[2], v1[3]);
;                     *(u32x4*)(P + (size_t)row * NIN + col) = w;
;                     if (u.pn >= 8 && u.pn < 16) {
;                         float* dst; int c2;
;                         if (u.pn < 12) { c2 = col - C_KB; dst = row < SEQ ? kp + (size_t)row * 1024 : ks + (size_t)(row - SEQ) * 1024; }
;                         else { c2 = col - C_VB; dst = row < SEQ ? vp + (size_t)row * 1024 : vs + (size_t)(row - SEQ) * 1024; }
;                         __builtin_nontemporal_store(v0, (f32x4*)(dst + c2)); __builtin_nontemporal_store(v1, (f32x4*)(dst + c2 + 4));
;                     }
.LBB0_966:
	s_nop 1
	v_mov_b32_e32 v4, v252
	v_add_u32_e32 v56, 0x90, v144
	v_ashrrev_i32_e32 v57, 31, v56
	v_mov_b64_e32 v[62:63], s[24:25]
	s_movk_i32 s10, 0x3f6f
	v_cmp_lt_i32_e64 s[10:11], s10, v144
	v_fmamk_f32 v4, v4, 0x3a800000, v236
	v_cmp_gt_f32_e32 vcc, s37, v4
	v_mul_f32_e32 v50, 0x4b800000, v4
	s_nop 0
	v_cndmask_b32_e32 v4, v4, v50, vcc
	v_rsq_f32_e32 v4, v4
	s_nop 0
	v_mul_f32_e32 v50, 0x45800000, v4
	v_cndmask_b32_e32 v54, v4, v50, vcc
	v_add_u32_e32 v4, 0xffffc090, v144
	v_lshlrev_b64 v[50:51], 12, v[56:57]
	v_mad_i64_i32 v[56:57], s[46:47], v56, s43, v[62:63]
	v_lshlrev_b64 v[52:53], 12, v[4:5]
	v_pk_mul_f32 v[48:49], v[48:49], v[54:55] op_sel_hi:[1,0]
	v_pk_mul_f32 v[46:47], v[46:47], v[54:55] op_sel_hi:[1,0]
	v_pk_mul_f32 v[44:45], v[44:45], v[54:55] op_sel_hi:[1,0]
	v_pk_mul_f32 v[42:43], v[42:43], v[54:55] op_sel_hi:[1,0]
	v_lshl_add_u64 v[56:57], v[142:143], 1, v[56:57]
	s_and_b64 vcc, exec, s[8:9]
	v_cvt_pk_bf16_f32 v58, v46, v47
	v_cvt_pk_bf16_f32 v59, v48, v49
	v_cvt_pk_bf16_f32 v60, v42, v43
	v_cvt_pk_bf16_f32 v61, v44, v45
	global_store_dwordx4 v[56:57], v[58:61], off
	s_cbranch_vccnz .LBB0_980
	s_and_b64 vcc, exec, s[6:7]
	s_mov_b64 s[46:47], -1
	s_cbranch_vccnz .LBB0_973
	s_and_saveexec_b64 s[46:47], s[10:11]
	s_xor_b64 s[46:47], exec, s[46:47]
	v_lshl_add_u64 v[58:59], s[30:31], 0, v[52:53]
	s_andn2_saveexec_b64 s[46:47], s[46:47]
	v_lshl_add_u64 v[58:59], s[28:29], 0, v[50:51]
	s_or_b64 exec, exec, s[46:47]
	v_add_u32_e32 v60, 0xfffff400, v142
	s_mov_b64 s[46:47], 0

; __device__ __forceinline__ unsigned cvt_pk_bf16(float lo, float hi) { unsigned r; asm("v_cvt_pk_bf16_f32 %0, %1, %2" : "=v"(r) : "v"(lo), "v"(hi)); return r; }
;     __device__ __forceinline__ void operator()(const f32x4 (&acc)[2][2][4][2], const Unit& u, int wr, int wc, int fr, int fq) const {
;     ...
;             for (int m = 0; m < 4; ++m) {
;                 const int row = row0 + ai * 128 + m * 16; const float rs = rsqrtf(sumsq[row] * (1.f / 1024.f) + EPS);
; #pragma unroll
;                 for (int bj = 0; bj < 2; ++bj) {
;                     const f32x4 v0 = acc[ai][bj][m][0] * rs, v1 = acc[ai][bj][m][1] * rs; const int col = colt + bj * 128;
;                     u32x4 w; w.x = cvt_pk_bf16(v0[0], v0[1]); w.y = cvt_pk_bf16(v0[2], v0[3]); w.z = cvt_pk_bf16(v1[0], v1[1]); w.w = cvt_pk_bf16(v1[2], v1[3]);
;                     *(u32x4*)(P + (size_t)row * NIN + col) = w;
;                     if (u.pn >= 8 && u.pn < 16) {
;                         float* dst; int c2;
;                         if (u.pn < 12) { c2 = col - C_KB; dst = row < SEQ ? kp + (size_t)row * 1024 : ks + (size_t)(row - SEQ) * 1024; }
;                         else { c2 = col - C_VB; dst = row < SEQ ? vp + (size_t)row * 1024 : vs + (size_t)(row - SEQ) * 1024; }
;                         __builtin_nontemporal_store(v0, (f32x4*)(dst + c2)); __builtin_nontemporal_store(v1, (f32x4*)(dst + c2 + 4));
;                     }
.LBB0_994:
	s_nop 1
	v_mov_b32_e32 v4, v253
	v_add_u32_e32 v40, 0xa0, v144
	v_ashrrev_i32_e32 v41, 31, v40
	v_mov_b64_e32 v[46:47], s[24:25]
	s_movk_i32 s10, 0x3f5f
	v_cmp_lt_i32_e64 s[10:11], s10, v144
	v_fmamk_f32 v4, v4, 0x3a800000, v236
	v_cmp_gt_f32_e32 vcc, s37, v4
	v_mul_f32_e32 v34, 0x4b800000, v4
	s_nop 0
	v_cndmask_b32_e32 v4, v4, v34, vcc
	v_rsq_f32_e32 v4, v4
	s_nop 0
	v_mul_f32_e32 v34, 0x45800000, v4
	v_cndmask_b32_e32 v38, v4, v34, vcc
	v_add_u32_e32 v4, 0xffffc0a0, v144
	v_lshlrev_b64 v[34:35], 12, v[40:41]
	v_mad_i64_i32 v[40:41], s[46:47], v40, s43, v[46:47]
	v_lshlrev_b64 v[36:37], 12, v[4:5]
	v_pk_mul_f32 v[32:33], v[32:33], v[38:39] op_sel_hi:[1,0]
	v_pk_mul_f32 v[30:31], v[30:31], v[38:39] op_sel_hi:[1,0]
	v_pk_mul_f32 v[28:29], v[28:29], v[38:39] op_sel_hi:[1,0]
	v_pk_mul_f32 v[26:27], v[26:27], v[38:39] op_sel_hi:[1,0]
	v_lshl_add_u64 v[40:41], v[142:143], 1, v[40:41]
	s_and_b64 vcc, exec, s[8:9]
	v_cvt_pk_bf16_f32 v42, v30, v31
	v_cvt_pk_bf16_f32 v43, v32, v33
	v_cvt_pk_bf16_f32 v44, v26, v27
	v_cvt_pk_bf16_f32 v45, v28, v29
	global_store_dwordx4 v[40:41], v[42:45], off
	s_cbranch_vccnz .LBB0_1008
	s_and_b64 vcc, exec, s[6:7]
	s_mov_b64 s[46:47], -1
	s_cbranch_vccnz .LBB0_1001
	s_and_saveexec_b64 s[46:47], s[10:11]
	s_xor_b64 s[46:47], exec, s[46:47]
	v_lshl_add_u64 v[42:43], s[30:31], 0, v[36:37]
	s_andn2_saveexec_b64 s[46:47], s[46:47]
	v_lshl_add_u64 v[42:43], s[28:29], 0, v[34:35]
	s_or_b64 exec, exec, s[46:47]
	v_add_u32_e32 v44, 0xfffff400, v142
	s_mov_b64 s[46:47], 0

; __device__ __forceinline__ unsigned cvt_pk_bf16(float lo, float hi) { unsigned r; asm("v_cvt_pk_bf16_f32 %0, %1, %2" : "=v"(r) : "v"(lo), "v"(hi)); return r; }
;     __device__ __forceinline__ void operator()(const f32x4 (&acc)[2][2][4][2], const Unit& u, int wr, int wc, int fr, int fq) const {
;     ...
;             for (int m = 0; m < 4; ++m) {
;                 const int row = row0 + ai * 128 + m * 16; const float rs = rsqrtf(sumsq[row] * (1.f / 1024.f) + EPS);
; #pragma unroll
;                 for (int bj = 0; bj < 2; ++bj) {
;                     const f32x4 v0 = acc[ai][bj][m][0] * rs, v1 = acc[ai][bj][m][1] * rs; const int col = colt + bj * 128;
;                     u32x4 w; w.x = cvt_pk_bf16(v0[0], v0[1]); w.y = cvt_pk_bf16(v0[2], v0[3]); w.z = cvt_pk_bf16(v1[0], v1[1]); w.w = cvt_pk_bf16(v1[2], v1[3]);
;                     *(u32x4*)(P + (size_t)row * NIN + col) = w;
;                     if (u.pn >= 8 && u.pn < 16) {
;                         float* dst; int c2;
;                         if (u.pn < 12) { c2 = col - C_KB; dst = row < SEQ ? kp + (size_t)row * 1024 : ks + (size_t)(row - SEQ) * 1024; }
;                         else { c2 = col - C_VB; dst = row < SEQ ? vp + (size_t)row * 1024 : vs + (size_t)(row - SEQ) * 1024; }
;                         __builtin_nontemporal_store(v0, (f32x4*)(dst + c2)); __builtin_nontemporal_store(v1, (f32x4*)(dst + c2 + 4));
;                     }
.LBB0_1022:
	s_nop 1
	v_mov_b32_e32 v24, v254
	v_add_u32_e32 v4, 0xffffc0b0, v144
	v_lshlrev_b64 v[20:21], 12, v[4:5]
	v_add_u32_e32 v18, 0xb0, v144
	v_mov_b64_e32 v[22:23], s[24:25]
	s_movk_i32 s10, 0x3f4f
	v_ashrrev_i32_e32 v19, 31, v18
	v_mad_i64_i32 v[22:23], s[46:47], v18, s43, v[22:23]
	v_cmp_lt_i32_e64 s[10:11], s10, v144
	v_lshlrev_b64 v[18:19], 12, v[18:19]
	v_lshl_add_u64 v[22:23], v[142:143], 1, v[22:23]
	v_fmamk_f32 v4, v24, 0x3a800000, v236
	v_mul_f32_e32 v24, 0x4b800000, v4
	v_cmp_gt_f32_e32 vcc, s37, v4
	s_nop 1
	v_cndmask_b32_e32 v4, v4, v24, vcc
	v_rsq_f32_e32 v4, v4
	s_nop 0
	v_mul_f32_e32 v24, 0x45800000, v4
	v_cndmask_b32_e32 v24, v4, v24, vcc
	v_pk_mul_f32 v[16:17], v[16:17], v[24:25] op_sel_hi:[1,0]
	v_pk_mul_f32 v[14:15], v[14:15], v[24:25] op_sel_hi:[1,0]
	v_pk_mul_f32 v[12:13], v[12:13], v[24:25] op_sel_hi:[1,0]
	v_pk_mul_f32 v[10:11], v[10:11], v[24:25] op_sel_hi:[1,0]
	s_and_b64 vcc, exec, s[8:9]
	v_cvt_pk_bf16_f32 v26, v14, v15
	v_cvt_pk_bf16_f32 v27, v16, v17
	v_cvt_pk_bf16_f32 v28, v10, v11
	v_cvt_pk_bf16_f32 v29, v12, v13
	global_store_dwordx4 v[22:23], v[26:29], off
	s_cbranch_vccnz .LBB0_1036
	s_and_b64 vcc, exec, s[6:7]
	s_mov_b64 s[46:47], -1
	s_cbranch_vccnz .LBB0_1029
	s_and_saveexec_b64 s[46:47], s[10:11]
	s_xor_b64 s[46:47], exec, s[46:47]
	v_lshl_add_u64 v[26:27], s[30:31], 0, v[20:21]
	s_andn2_saveexec_b64 s[46:47], s[46:47]
	v_lshl_add_u64 v[26:27], s[28:29], 0, v[18:19]
	s_or_b64 exec, exec, s[46:47]
	v_add_u32_e32 v28, 0xfffff400, v142
	s_mov_b64 s[46:47], 0

; __global__ void __launch_bounds__(512, 2) fwd_kernel(Params p_arg) {
	.amdhsa_kernel _Z10fwd_kernel6Params
		.amdhsa_group_segment_fixed_size 0
		.amdhsa_private_segment_fixed_size 0
		.amdhsa_kernarg_size 672
		.amdhsa_user_sgpr_count 2
		.amdhsa_user_sgpr_dispatch_ptr 0
		.amdhsa_user_sgpr_queue_ptr 0
		.amdhsa_user_sgpr_kernarg_segment_ptr 1
		.amdhsa_user_sgpr_dispatch_id 0
		.amdhsa_user_sgpr_kernarg_preload_length 0
		.amdhsa_user_sgpr_kernarg_preload_offset 0
		.amdhsa_user_sgpr_private_segment_size 0
		.amdhsa_uses_dynamic_stack 0
		.amdhsa_enable_private_segment 0
		.amdhsa_system_sgpr_workgroup_id_x 1
		.amdhsa_system_sgpr_workgroup_id_y 0
		.amdhsa_system_sgpr_workgroup_id_z 0
		.amdhsa_system_sgpr_workgroup_info 0
		.amdhsa_system_vgpr_workitem_id 2
		.amdhsa_next_free_vgpr 256
		.amdhsa_next_free_sgpr 100
		.amdhsa_accum_offset 256
		.amdhsa_reserve_vcc 1
		.amdhsa_float_round_mode_32 0
		.amdhsa_float_round_mode_16_64 0
		.amdhsa_float_denorm_mode_32 3
		.amdhsa_float_denorm_mode_16_64 3
		.amdhsa_dx10_clamp 1
		.amdhsa_ieee_mode 1
		.amdhsa_fp16_overflow 0
		.amdhsa_tg_split 0
		.amdhsa_exception_fp_ieee_invalid_op 0
		.amdhsa_exception_fp_denorm_src 0
		.amdhsa_exception_fp_ieee_div_zero 0
		.amdhsa_exception_fp_ieee_overflow 0
		.amdhsa_exception_fp_ieee_underflow 0
		.amdhsa_exception_fp_ieee_inexact 0
		.amdhsa_exception_int_div_zero 0
	.end_amdhsa_kernel

; __global__ void __launch_bounds__(512, 2) fwd_kernel(Params p_arg) {
amdhsa.kernels:
  - .agpr_count:     0
    .args:
      - .offset:         0
        .size:           416
        .value_kind:     by_value
      - .offset:         416
        .size:           4
        .value_kind:     hidden_block_count_x
      - .offset:         420
        .size:           4
        .value_kind:     hidden_block_count_y
      - .offset:         424
        .size:           4
        .value_kind:     hidden_block_count_z
      - .offset:         428
        .size:           2
        .value_kind:     hidden_group_size_x
      - .offset:         430
        .size:           2
        .value_kind:     hidden_group_size_y
      - .offset:         432
        .size:           2
        .value_kind:     hidden_group_size_z
      - .offset:         434
        .size:           2
        .value_kind:     hidden_remainder_x
      - .offset:         436
        .size:           2
        .value_kind:     hidden_remainder_y
      - .offset:         438
        .size:           2
        .value_kind:     hidden_remainder_z
      - .offset:         456
        .size:           8
        .value_kind:     hidden_global_offset_x
      - .offset:         464
        .size:           8
        .value_kind:     hidden_global_offset_y
      - .offset:         472
        .size:           8
        .value_kind:     hidden_global_offset_z
      - .offset:         480
        .size:           2
        .value_kind:     hidden_grid_dims
      - .offset:         504
        .size:           8
        .value_kind:     hidden_multigrid_sync_arg
      - .offset:         536
        .size:           4
        .value_kind:     hidden_dynamic_lds_size
    .group_segment_fixed_size: 0
    .kernarg_segment_align: 8
    .kernarg_segment_size: 672
    .language:       OpenCL C
    .language_version:
      - 2
      - 0
    .max_flat_workgroup_size: 512
    .name:           _Z10fwd_kernel6Params
    .private_segment_fixed_size: 0
    .sgpr_count:     106
    .sgpr_spill_count: 26
    .symbol:         _Z10fwd_kernel6Params.kd
    .uniform_work_group_size: 1
    .uses_dynamic_stack: false
    .vgpr_count:     256
    .vgpr_spill_count: 0
    .wavefront_size: 64
